# hyena filter generation: a3 loads pipelined 5 deep
# baseline (speedup 1.0000x reference)
; __device__ __forceinline__ void phase_hyena(KP kp_, int hf){ asm volatile("" : "+s"(kp_)); const Params p=load_params(kp_);
;     ...
;       int n=lane&15, kg=lane>>4;
;       f16x8 bw0, bw1;
;       _Pragma("unroll") for (int e=0;e<8;++e){ bw0[e]=(n<4)?(_Float16)misc[(kg*8+e)*4+n]:(_Float16)0.f; bw1[e]=(n<4)?(_Float16)misc[(32+kg*8+e)*4+n]:(_Float16)0.f; }
;       const float dsc=-delta*(1.f/8191.f);
;       float pj0=__expf(dsc*(float)(kg*4)), pj1=__expf(dsc*(float)(kg*4+1)), pj2=__expf(dsc*(float)(kg*4+2)), pj3=__expf(dsc*(float)(kg*4+3));
;       float* Zf=(float*)Z; float ssl=0.f; int order=n&1; bool side1=(n&2)!=0;
;       _Pragma("unroll 8") for (int i=0;i<64;++i){ int tl=wid+8*i;
;         const _Float16* ap=a3+(size_t)(tl*16+n)*64+kg*8;
;         f16x8 a0=*(const f16x8*)ap, a1=*(const f16x8*)(ap+32);
;         f32x4 dd={0.f,0.f,0.f,0.f};
;         dd=__builtin_amdgcn_mfma_f32_16x16x32_f16(a0,bw0,dd,0,0,0);
;         dd=__builtin_amdgcn_mfma_f32_16x16x32_f16(a1,bw1,dd,0,0,0);
;         if (n<4){ float d0=__expf(dsc*(float)(tl*16)); int lag0=tl*16+kg*4;
;           float v0=dd[0]*d0*pj0, v1=dd[1]*d0*pj1, v2=dd[2]*d0*pj2, v3=dd[3]*d0*pj3;
;           if (!side1){ Zf[2*(lag0)+order]=v0; Zf[2*(lag0+1)+order]=v1; Zf[2*(lag0+2)+order]=v2; Zf[2*(lag0+3)+order]=v3; ssl+=v0*v0+v1*v1+v2*v2+v3*v3; }
;           else { if (lag0>=1){ Zf[2*(16384-lag0)+order]=v0; ssl+=v0*v0; }
;             Zf[2*(16384-lag0-1)+order]=v1; Zf[2*(16384-lag0-2)+order]=v2; Zf[2*(16384-lag0-3)+order]=v3; ssl+=v1*v1+v2*v2+v3*v3; } }
.LBB0_1232:
	s_or_b64 exec, exec, s[12:13]
	v_perm_b32 v3, v15, v3, s82
	v_perm_b32 v2, v7, v2, s82
	v_perm_b32 v1, v6, v1, s82
	v_perm_b32 v0, v5, v0, s82
	v_perm_b32 v7, v14, v13, s82
	v_perm_b32 v6, v12, v11, s82
	v_perm_b32 v5, v10, v9, s82
	v_perm_b32 v4, v8, v4, s82
	v_and_b32_e32 v222, 63, v154
	v_and_b32_e32 v223, 15, v222
	v_lshrrev_b32_e32 v224, 4, v222
	v_lshrrev_b32_e32 v29, 6, v154
	v_lshlrev_b32_e32 v85, 11, v29
	v_lshl_add_u32 v85, v223, 7, v85
	v_lshl_add_u32 v85, v224, 4, v85
	v_add_u32_e32 v85, 0x3b89000, v85
	global_load_dwordx4 v[228:231], v85, s[70:71]
	global_load_dwordx4 v[232:235], v85, s[70:71] offset:64
	v_add_u32_e32 v85, 0x4000, v85
	global_load_dwordx4 v[236:239], v85, s[70:71]
	global_load_dwordx4 v[240:243], v85, s[70:71] offset:64
	v_add_u32_e32 v85, 0x4000, v85
	global_load_dwordx4 v[244:247], v85, s[70:71]
	global_load_dwordx4 v[248:251], v85, s[70:71] offset:64
	v_add_u32_e32 v85, 0x4000, v85
	global_load_dwordx4 v[12:15], v85, s[70:71]
	global_load_dwordx4 v[16:19], v85, s[70:71] offset:64
	v_add_u32_e32 v85, 0x4000, v85
	global_load_dwordx4 v[20:23], v85, s[70:71]
	global_load_dwordx4 v[24:27], v85, s[70:71] offset:64
	v_add_u32_e32 v85, 0x4000, v85
	v_lshlrev_b32_e32 v78, 7, v29
	v_lshl_add_u32 v78, v224, 5, v78
	v_and_b32_e32 v227, 1, v223
	v_lshlrev_b32_e32 v227, 2, v227
	v_sub_u32_e32 v79, 0x1ffe8, v78
	v_add_u32_e32 v78, v78, v227
	v_add_u32_e32 v79, v79, v227
	v_cndmask_b32_e64 v78, v78, v79, s[40:41]
	v_mov_b32_e32 v227, 0x400
	v_mov_b32_e32 v79, 0xfffffc00
	v_cndmask_b32_e64 v79, v227, v79, s[40:41]
	v_cndmask_b32_e64 v80, v95, v50, s[40:41]
	v_cndmask_b32_e64 v81, v51, v96, s[40:41]
	v_cndmask_b32_e64 v82, v96, v51, s[40:41]
	v_cndmask_b32_e64 v84, v50, v95, s[40:41]
	v_lshrrev_b32_e32 v227, 4, v154
	v_cmp_eq_u32_e64 s[100:101], 0, v227
	s_nop 3
	s_and_b64 s[100:101], s[100:101], s[40:41]
	s_and_b64 s[100:101], s[100:101], s[38:39]
	v_mov_b32_e32 v30, 1.0
	s_nop 1
	v_cndmask_b32_e64 v30, v30, 0, s[100:101]
	s_andn2_b64 s[100:101], s[38:39], s[100:101]
	v_lshlrev_b32_e32 v29, 4, v29
	v_mov_b32_e32 v28, 0
	v_mov_b32_e32 v227, v29
	v_cvt_f32_i32_e32 v227, v227
	v_mul_f32_e32 v227, v93, v227
	v_mul_f32_e32 v227, 0x3fb8aa3b, v227
	v_exp_f32_e32 v226, v227
	s_waitcnt vmcnt(8)
	v_mfma_f32_16x16x32_f16 v[8:11], v[228:231], v[0:3], 0
	v_mfma_f32_16x16x32_f16 v[8:11], v[232:235], v[4:7], v[8:11]
	global_load_dwordx4 v[228:231], v85, s[70:71]
	global_load_dwordx4 v[232:235], v85, s[70:71] offset:64
	v_add_u32_e32 v85, 0x4000, v85
	s_nop 4
	v_cndmask_b32_e64 v222, v8, v11, s[40:41]
	v_cndmask_b32_e64 v223, v9, v10, s[40:41]
	v_cndmask_b32_e64 v224, v10, v9, s[40:41]
	v_cndmask_b32_e64 v225, v11, v8, s[40:41]
	v_mul_f32_e32 v222, v222, v226
	v_mul_f32_e32 v223, v223, v226
	v_mul_f32_e32 v224, v224, v226
	v_mul_f32_e32 v225, v225, v226
	v_mul_f32_e32 v222, v80, v222
	v_mul_f32_e32 v223, v81, v223
	v_mul_f32_e32 v224, v82, v224
	v_mul_f32_e32 v225, v84, v225
	v_mul_f32_e32 v31, v222, v222
	v_fmac_f32_e32 v31, v223, v223
	v_fmac_f32_e32 v31, v224, v224
	v_mul_f32_e32 v227, v225, v30
	v_fmac_f32_e32 v31, v227, v227
	v_add_f32_e32 v28, v28, v31
	s_mov_b64 exec, s[38:39]
	ds_write_b32 v78, v222
	ds_write_b32 v78, v223 offset:8
	ds_write_b32 v78, v224 offset:16
	s_mov_b64 exec, s[100:101]
	ds_write_b32 v78, v225 offset:24
	s_mov_b64 exec, -1
	v_add_u32_e32 v78, v78, v79
	v_add_u32_e32 v227, 0x80, v29
	v_cvt_f32_i32_e32 v227, v227
	v_mul_f32_e32 v227, v93, v227
	v_mul_f32_e32 v227, 0x3fb8aa3b, v227
	v_exp_f32_e32 v226, v227
	s_waitcnt vmcnt(8)
	v_mfma_f32_16x16x32_f16 v[8:11], v[236:239], v[0:3], 0
	v_mfma_f32_16x16x32_f16 v[8:11], v[240:243], v[4:7], v[8:11]
	global_load_dwordx4 v[236:239], v85, s[70:71]
	global_load_dwordx4 v[240:243], v85, s[70:71] offset:64
	v_add_u32_e32 v85, 0x4000, v85
	s_nop 4
	v_cndmask_b32_e64 v222, v8, v11, s[40:41]
	v_cndmask_b32_e64 v223, v9, v10, s[40:41]
	v_cndmask_b32_e64 v224, v10, v9, s[40:41]
	v_cndmask_b32_e64 v225, v11, v8, s[40:41]
	v_mul_f32_e32 v222, v222, v226
	v_mul_f32_e32 v223, v223, v226
	v_mul_f32_e32 v224, v224, v226
	v_mul_f32_e32 v225, v225, v226
	v_mul_f32_e32 v222, v80, v222
	v_mul_f32_e32 v223, v81, v223
	v_mul_f32_e32 v224, v82, v224
	v_mul_f32_e32 v225, v84, v225
	v_mul_f32_e32 v31, v222, v222
	v_fmac_f32_e32 v31, v223, v223
	v_fmac_f32_e32 v31, v224, v224
	v_fmac_f32_e32 v31, v225, v225
	v_add_f32_e32 v28, v28, v31
	s_mov_b64 exec, s[38:39]
	ds_write_b32 v78, v222
	ds_write_b32 v78, v223 offset:8
	ds_write_b32 v78, v224 offset:16
	ds_write_b32 v78, v225 offset:24
	s_mov_b64 exec, -1
	v_add_u32_e32 v78, v78, v79
	v_add_u32_e32 v227, 0x100, v29
	v_cvt_f32_i32_e32 v227, v227
	v_mul_f32_e32 v227, v93, v227
	v_mul_f32_e32 v227, 0x3fb8aa3b, v227
	v_exp_f32_e32 v226, v227
	s_waitcnt vmcnt(8)
	v_mfma_f32_16x16x32_f16 v[8:11], v[244:247], v[0:3], 0
	v_mfma_f32_16x16x32_f16 v[8:11], v[248:251], v[4:7], v[8:11]
	global_load_dwordx4 v[244:247], v85, s[70:71]
	global_load_dwordx4 v[248:251], v85, s[70:71] offset:64
	v_add_u32_e32 v85, 0x4000, v85
	s_nop 4
	v_cndmask_b32_e64 v222, v8, v11, s[40:41]
	v_cndmask_b32_e64 v223, v9, v10, s[40:41]
	v_cndmask_b32_e64 v224, v10, v9, s[40:41]
	v_cndmask_b32_e64 v225, v11, v8, s[40:41]
	v_mul_f32_e32 v222, v222, v226
	v_mul_f32_e32 v223, v223, v226
	v_mul_f32_e32 v224, v224, v226
	v_mul_f32_e32 v225, v225, v226
	v_mul_f32_e32 v222, v80, v222
	v_mul_f32_e32 v223, v81, v223
	v_mul_f32_e32 v224, v82, v224
	v_mul_f32_e32 v225, v84, v225
	v_mul_f32_e32 v31, v222, v222
	v_fmac_f32_e32 v31, v223, v223
	v_fmac_f32_e32 v31, v224, v224
	v_fmac_f32_e32 v31, v225, v225
	v_add_f32_e32 v28, v28, v31
	s_mov_b64 exec, s[38:39]
	ds_write_b32 v78, v222
	ds_write_b32 v78, v223 offset:8
	ds_write_b32 v78, v224 offset:16
	ds_write_b32 v78, v225 offset:24
	s_mov_b64 exec, -1
	v_add_u32_e32 v78, v78, v79
	v_add_u32_e32 v227, 0x180, v29
	v_cvt_f32_i32_e32 v227, v227
	v_mul_f32_e32 v227, v93, v227
	v_mul_f32_e32 v227, 0x3fb8aa3b, v227
	v_exp_f32_e32 v226, v227
	s_waitcnt vmcnt(8)
; __device__ __forceinline__ void phase_hyena(KP kp_, int hf){ asm volatile("" : "+s"(kp_)); const Params p=load_params(kp_);
;     ...
;       _Pragma("unroll 8") for (int i=0;i<64;++i){ int tl=wid+8*i;
;         const _Float16* ap=a3+(size_t)(tl*16+n)*64+kg*8;
;         f16x8 a0=*(const f16x8*)ap, a1=*(const f16x8*)(ap+32);
;         f32x4 dd={0.f,0.f,0.f,0.f};
;         dd=__builtin_amdgcn_mfma_f32_16x16x32_f16(a0,bw0,dd,0,0,0);
;         dd=__builtin_amdgcn_mfma_f32_16x16x32_f16(a1,bw1,dd,0,0,0);
;         if (n<4){ float d0=__expf(dsc*(float)(tl*16)); int lag0=tl*16+kg*4;
;           float v0=dd[0]*d0*pj0, v1=dd[1]*d0*pj1, v2=dd[2]*d0*pj2, v3=dd[3]*d0*pj3;
;           if (!side1){ Zf[2*(lag0)+order]=v0; Zf[2*(lag0+1)+order]=v1; Zf[2*(lag0+2)+order]=v2; Zf[2*(lag0+3)+order]=v3; ssl+=v0*v0+v1*v1+v2*v2+v3*v3; }
;           else { if (lag0>=1){ Zf[2*(16384-lag0)+order]=v0; ssl+=v0*v0; }
;             Zf[2*(16384-lag0-1)+order]=v1; Zf[2*(16384-lag0-2)+order]=v2; Zf[2*(16384-lag0-3)+order]=v3; ssl+=v1*v1+v2*v2+v3*v3; } }
	v_mfma_f32_16x16x32_f16 v[8:11], v[12:15], v[0:3], 0
	v_mfma_f32_16x16x32_f16 v[8:11], v[16:19], v[4:7], v[8:11]
	global_load_dwordx4 v[12:15], v85, s[70:71]
	global_load_dwordx4 v[16:19], v85, s[70:71] offset:64
	v_add_u32_e32 v85, 0x4000, v85
	s_nop 4
	v_cndmask_b32_e64 v222, v8, v11, s[40:41]
	v_cndmask_b32_e64 v223, v9, v10, s[40:41]
	v_cndmask_b32_e64 v224, v10, v9, s[40:41]
	v_cndmask_b32_e64 v225, v11, v8, s[40:41]
	v_mul_f32_e32 v222, v222, v226
	v_mul_f32_e32 v223, v223, v226
	v_mul_f32_e32 v224, v224, v226
	v_mul_f32_e32 v225, v225, v226
	v_mul_f32_e32 v222, v80, v222
	v_mul_f32_e32 v223, v81, v223
	v_mul_f32_e32 v224, v82, v224
	v_mul_f32_e32 v225, v84, v225
	v_mul_f32_e32 v31, v222, v222
	v_fmac_f32_e32 v31, v223, v223
	v_fmac_f32_e32 v31, v224, v224
	v_fmac_f32_e32 v31, v225, v225
	v_add_f32_e32 v28, v28, v31
	s_mov_b64 exec, s[38:39]
	ds_write_b32 v78, v222
	ds_write_b32 v78, v223 offset:8
	ds_write_b32 v78, v224 offset:16
	ds_write_b32 v78, v225 offset:24
	s_mov_b64 exec, -1
	v_add_u32_e32 v78, v78, v79
	v_add_u32_e32 v227, 0x200, v29
	v_cvt_f32_i32_e32 v227, v227
	v_mul_f32_e32 v227, v93, v227
	v_mul_f32_e32 v227, 0x3fb8aa3b, v227
	v_exp_f32_e32 v226, v227
	s_waitcnt vmcnt(8)
	v_mfma_f32_16x16x32_f16 v[8:11], v[20:23], v[0:3], 0
	v_mfma_f32_16x16x32_f16 v[8:11], v[24:27], v[4:7], v[8:11]
	global_load_dwordx4 v[20:23], v85, s[70:71]
	global_load_dwordx4 v[24:27], v85, s[70:71] offset:64
	v_add_u32_e32 v85, 0x4000, v85
	s_nop 4
	v_cndmask_b32_e64 v222, v8, v11, s[40:41]
	v_cndmask_b32_e64 v223, v9, v10, s[40:41]
	v_cndmask_b32_e64 v224, v10, v9, s[40:41]
	v_cndmask_b32_e64 v225, v11, v8, s[40:41]
	v_mul_f32_e32 v222, v222, v226
	v_mul_f32_e32 v223, v223, v226
	v_mul_f32_e32 v224, v224, v226
	v_mul_f32_e32 v225, v225, v226
	v_mul_f32_e32 v222, v80, v222
	v_mul_f32_e32 v223, v81, v223
	v_mul_f32_e32 v224, v82, v224
	v_mul_f32_e32 v225, v84, v225
	v_mul_f32_e32 v31, v222, v222
	v_fmac_f32_e32 v31, v223, v223
	v_fmac_f32_e32 v31, v224, v224
	v_fmac_f32_e32 v31, v225, v225
	v_add_f32_e32 v28, v28, v31
	s_mov_b64 exec, s[38:39]
	ds_write_b32 v78, v222
	ds_write_b32 v78, v223 offset:8
	ds_write_b32 v78, v224 offset:16
	ds_write_b32 v78, v225 offset:24
	s_mov_b64 exec, -1
	v_add_u32_e32 v78, v78, v79
	v_add_u32_e32 v227, 0x280, v29
	v_cvt_f32_i32_e32 v227, v227
	v_mul_f32_e32 v227, v93, v227
	v_mul_f32_e32 v227, 0x3fb8aa3b, v227
	v_exp_f32_e32 v226, v227
	s_waitcnt vmcnt(8)
	v_mfma_f32_16x16x32_f16 v[8:11], v[228:231], v[0:3], 0
	v_mfma_f32_16x16x32_f16 v[8:11], v[232:235], v[4:7], v[8:11]
	global_load_dwordx4 v[228:231], v85, s[70:71]
	global_load_dwordx4 v[232:235], v85, s[70:71] offset:64
	v_add_u32_e32 v85, 0x4000, v85
	s_nop 4
	v_cndmask_b32_e64 v222, v8, v11, s[40:41]
	v_cndmask_b32_e64 v223, v9, v10, s[40:41]
	v_cndmask_b32_e64 v224, v10, v9, s[40:41]
	v_cndmask_b32_e64 v225, v11, v8, s[40:41]
	v_mul_f32_e32 v222, v222, v226
	v_mul_f32_e32 v223, v223, v226
	v_mul_f32_e32 v224, v224, v226
	v_mul_f32_e32 v225, v225, v226
	v_mul_f32_e32 v222, v80, v222
	v_mul_f32_e32 v223, v81, v223
	v_mul_f32_e32 v224, v82, v224
	v_mul_f32_e32 v225, v84, v225
	v_mul_f32_e32 v31, v222, v222
	v_fmac_f32_e32 v31, v223, v223
	v_fmac_f32_e32 v31, v224, v224
	v_fmac_f32_e32 v31, v225, v225
	v_add_f32_e32 v28, v28, v31
	s_mov_b64 exec, s[38:39]
	ds_write_b32 v78, v222
	ds_write_b32 v78, v223 offset:8
	ds_write_b32 v78, v224 offset:16
	ds_write_b32 v78, v225 offset:24
	s_mov_b64 exec, -1
	v_add_u32_e32 v78, v78, v79
	v_add_u32_e32 v227, 0x300, v29
	v_cvt_f32_i32_e32 v227, v227
	v_mul_f32_e32 v227, v93, v227
	v_mul_f32_e32 v227, 0x3fb8aa3b, v227
	v_exp_f32_e32 v226, v227
	s_waitcnt vmcnt(8)
	v_mfma_f32_16x16x32_f16 v[8:11], v[236:239], v[0:3], 0
	v_mfma_f32_16x16x32_f16 v[8:11], v[240:243], v[4:7], v[8:11]
	global_load_dwordx4 v[236:239], v85, s[70:71]
	global_load_dwordx4 v[240:243], v85, s[70:71] offset:64
	v_add_u32_e32 v85, 0x4000, v85
	s_nop 4
	v_cndmask_b32_e64 v222, v8, v11, s[40:41]
	v_cndmask_b32_e64 v223, v9, v10, s[40:41]
	v_cndmask_b32_e64 v224, v10, v9, s[40:41]
	v_cndmask_b32_e64 v225, v11, v8, s[40:41]
	v_mul_f32_e32 v222, v222, v226
	v_mul_f32_e32 v223, v223, v226
	v_mul_f32_e32 v224, v224, v226
	v_mul_f32_e32 v225, v225, v226
	v_mul_f32_e32 v222, v80, v222
	v_mul_f32_e32 v223, v81, v223
	v_mul_f32_e32 v224, v82, v224
	v_mul_f32_e32 v225, v84, v225
	v_mul_f32_e32 v31, v222, v222
	v_fmac_f32_e32 v31, v223, v223
	v_fmac_f32_e32 v31, v224, v224
	v_fmac_f32_e32 v31, v225, v225
	v_add_f32_e32 v28, v28, v31
	s_mov_b64 exec, s[38:39]
	ds_write_b32 v78, v222
	ds_write_b32 v78, v223 offset:8
	ds_write_b32 v78, v224 offset:16
	ds_write_b32 v78, v225 offset:24
	s_mov_b64 exec, -1
	v_add_u32_e32 v78, v78, v79
	v_add_u32_e32 v227, 0x380, v29
	v_cvt_f32_i32_e32 v227, v227
	v_mul_f32_e32 v227, v93, v227
	v_mul_f32_e32 v227, 0x3fb8aa3b, v227
	v_exp_f32_e32 v226, v227
	s_waitcnt vmcnt(8)
	v_mfma_f32_16x16x32_f16 v[8:11], v[244:247], v[0:3], 0
	v_mfma_f32_16x16x32_f16 v[8:11], v[248:251], v[4:7], v[8:11]
	global_load_dwordx4 v[244:247], v85, s[70:71]
	global_load_dwordx4 v[248:251], v85, s[70:71] offset:64
	v_add_u32_e32 v85, 0x4000, v85
	s_nop 4
	v_cndmask_b32_e64 v222, v8, v11, s[40:41]
	v_cndmask_b32_e64 v223, v9, v10, s[40:41]
	v_cndmask_b32_e64 v224, v10, v9, s[40:41]
	v_cndmask_b32_e64 v225, v11, v8, s[40:41]
	v_mul_f32_e32 v222, v222, v226
	v_mul_f32_e32 v223, v223, v226
	v_mul_f32_e32 v224, v224, v226
	v_mul_f32_e32 v225, v225, v226
	v_mul_f32_e32 v222, v80, v222
	v_mul_f32_e32 v223, v81, v223
	v_mul_f32_e32 v224, v82, v224
	v_mul_f32_e32 v225, v84, v225
	v_mul_f32_e32 v31, v222, v222
	v_fmac_f32_e32 v31, v223, v223
	v_fmac_f32_e32 v31, v224, v224
	v_fmac_f32_e32 v31, v225, v225
	v_add_f32_e32 v28, v28, v31
	s_mov_b64 exec, s[38:39]
	ds_write_b32 v78, v222
	ds_write_b32 v78, v223 offset:8
	ds_write_b32 v78, v224 offset:16
	ds_write_b32 v78, v225 offset:24
	s_mov_b64 exec, -1
	v_add_u32_e32 v78, v78, v79
	v_add_u32_e32 v227, 0x400, v29
	v_cvt_f32_i32_e32 v227, v227
	v_mul_f32_e32 v227, v93, v227
	v_mul_f32_e32 v227, 0x3fb8aa3b, v227
	v_exp_f32_e32 v226, v227
	s_waitcnt vmcnt(8)
; __device__ __forceinline__ void phase_hyena(KP kp_, int hf){ asm volatile("" : "+s"(kp_)); const Params p=load_params(kp_);
;     ...
;       _Pragma("unroll 8") for (int i=0;i<64;++i){ int tl=wid+8*i;
;         const _Float16* ap=a3+(size_t)(tl*16+n)*64+kg*8;
;         f16x8 a0=*(const f16x8*)ap, a1=*(const f16x8*)(ap+32);
;         f32x4 dd={0.f,0.f,0.f,0.f};
;         dd=__builtin_amdgcn_mfma_f32_16x16x32_f16(a0,bw0,dd,0,0,0);
;         dd=__builtin_amdgcn_mfma_f32_16x16x32_f16(a1,bw1,dd,0,0,0);
;         if (n<4){ float d0=__expf(dsc*(float)(tl*16)); int lag0=tl*16+kg*4;
;           float v0=dd[0]*d0*pj0, v1=dd[1]*d0*pj1, v2=dd[2]*d0*pj2, v3=dd[3]*d0*pj3;
;           if (!side1){ Zf[2*(lag0)+order]=v0; Zf[2*(lag0+1)+order]=v1; Zf[2*(lag0+2)+order]=v2; Zf[2*(lag0+3)+order]=v3; ssl+=v0*v0+v1*v1+v2*v2+v3*v3; }
;           else { if (lag0>=1){ Zf[2*(16384-lag0)+order]=v0; ssl+=v0*v0; }
;             Zf[2*(16384-lag0-1)+order]=v1; Zf[2*(16384-lag0-2)+order]=v2; Zf[2*(16384-lag0-3)+order]=v3; ssl+=v1*v1+v2*v2+v3*v3; } }
	v_mfma_f32_16x16x32_f16 v[8:11], v[12:15], v[0:3], 0
	v_mfma_f32_16x16x32_f16 v[8:11], v[16:19], v[4:7], v[8:11]
	global_load_dwordx4 v[12:15], v85, s[70:71]
	global_load_dwordx4 v[16:19], v85, s[70:71] offset:64
	v_add_u32_e32 v85, 0x4000, v85
	s_nop 4
	v_cndmask_b32_e64 v222, v8, v11, s[40:41]
	v_cndmask_b32_e64 v223, v9, v10, s[40:41]
	v_cndmask_b32_e64 v224, v10, v9, s[40:41]
	v_cndmask_b32_e64 v225, v11, v8, s[40:41]
	v_mul_f32_e32 v222, v222, v226
	v_mul_f32_e32 v223, v223, v226
	v_mul_f32_e32 v224, v224, v226
	v_mul_f32_e32 v225, v225, v226
	v_mul_f32_e32 v222, v80, v222
	v_mul_f32_e32 v223, v81, v223
	v_mul_f32_e32 v224, v82, v224
	v_mul_f32_e32 v225, v84, v225
	v_mul_f32_e32 v31, v222, v222
	v_fmac_f32_e32 v31, v223, v223
	v_fmac_f32_e32 v31, v224, v224
	v_fmac_f32_e32 v31, v225, v225
	v_add_f32_e32 v28, v28, v31
	s_mov_b64 exec, s[38:39]
	ds_write_b32 v78, v222
	ds_write_b32 v78, v223 offset:8
	ds_write_b32 v78, v224 offset:16
	ds_write_b32 v78, v225 offset:24
	s_mov_b64 exec, -1
	v_add_u32_e32 v78, v78, v79
	v_add_u32_e32 v227, 0x480, v29
	v_cvt_f32_i32_e32 v227, v227
	v_mul_f32_e32 v227, v93, v227
	v_mul_f32_e32 v227, 0x3fb8aa3b, v227
	v_exp_f32_e32 v226, v227
	s_waitcnt vmcnt(8)
	v_mfma_f32_16x16x32_f16 v[8:11], v[20:23], v[0:3], 0
	v_mfma_f32_16x16x32_f16 v[8:11], v[24:27], v[4:7], v[8:11]
	global_load_dwordx4 v[20:23], v85, s[70:71]
	global_load_dwordx4 v[24:27], v85, s[70:71] offset:64
	v_add_u32_e32 v85, 0x4000, v85
	s_nop 4
	v_cndmask_b32_e64 v222, v8, v11, s[40:41]
	v_cndmask_b32_e64 v223, v9, v10, s[40:41]
	v_cndmask_b32_e64 v224, v10, v9, s[40:41]
	v_cndmask_b32_e64 v225, v11, v8, s[40:41]
	v_mul_f32_e32 v222, v222, v226
	v_mul_f32_e32 v223, v223, v226
	v_mul_f32_e32 v224, v224, v226
	v_mul_f32_e32 v225, v225, v226
	v_mul_f32_e32 v222, v80, v222
	v_mul_f32_e32 v223, v81, v223
	v_mul_f32_e32 v224, v82, v224
	v_mul_f32_e32 v225, v84, v225
	v_mul_f32_e32 v31, v222, v222
	v_fmac_f32_e32 v31, v223, v223
	v_fmac_f32_e32 v31, v224, v224
	v_fmac_f32_e32 v31, v225, v225
	v_add_f32_e32 v28, v28, v31
	s_mov_b64 exec, s[38:39]
	ds_write_b32 v78, v222
	ds_write_b32 v78, v223 offset:8
	ds_write_b32 v78, v224 offset:16
	ds_write_b32 v78, v225 offset:24
	s_mov_b64 exec, -1
	v_add_u32_e32 v78, v78, v79
	v_add_u32_e32 v227, 0x500, v29
	v_cvt_f32_i32_e32 v227, v227
	v_mul_f32_e32 v227, v93, v227
	v_mul_f32_e32 v227, 0x3fb8aa3b, v227
	v_exp_f32_e32 v226, v227
	s_waitcnt vmcnt(8)
	v_mfma_f32_16x16x32_f16 v[8:11], v[228:231], v[0:3], 0
	v_mfma_f32_16x16x32_f16 v[8:11], v[232:235], v[4:7], v[8:11]
	global_load_dwordx4 v[228:231], v85, s[70:71]
	global_load_dwordx4 v[232:235], v85, s[70:71] offset:64
	v_add_u32_e32 v85, 0x4000, v85
	s_nop 4
	v_cndmask_b32_e64 v222, v8, v11, s[40:41]
	v_cndmask_b32_e64 v223, v9, v10, s[40:41]
	v_cndmask_b32_e64 v224, v10, v9, s[40:41]
	v_cndmask_b32_e64 v225, v11, v8, s[40:41]
	v_mul_f32_e32 v222, v222, v226
	v_mul_f32_e32 v223, v223, v226
	v_mul_f32_e32 v224, v224, v226
	v_mul_f32_e32 v225, v225, v226
	v_mul_f32_e32 v222, v80, v222
	v_mul_f32_e32 v223, v81, v223
	v_mul_f32_e32 v224, v82, v224
	v_mul_f32_e32 v225, v84, v225
	v_mul_f32_e32 v31, v222, v222
	v_fmac_f32_e32 v31, v223, v223
	v_fmac_f32_e32 v31, v224, v224
	v_fmac_f32_e32 v31, v225, v225
	v_add_f32_e32 v28, v28, v31
	s_mov_b64 exec, s[38:39]
	ds_write_b32 v78, v222
	ds_write_b32 v78, v223 offset:8
	ds_write_b32 v78, v224 offset:16
	ds_write_b32 v78, v225 offset:24
	s_mov_b64 exec, -1
	v_add_u32_e32 v78, v78, v79
	v_add_u32_e32 v227, 0x580, v29
	v_cvt_f32_i32_e32 v227, v227
	v_mul_f32_e32 v227, v93, v227
	v_mul_f32_e32 v227, 0x3fb8aa3b, v227
	v_exp_f32_e32 v226, v227
	s_waitcnt vmcnt(8)
	v_mfma_f32_16x16x32_f16 v[8:11], v[236:239], v[0:3], 0
	v_mfma_f32_16x16x32_f16 v[8:11], v[240:243], v[4:7], v[8:11]
	global_load_dwordx4 v[236:239], v85, s[70:71]
	global_load_dwordx4 v[240:243], v85, s[70:71] offset:64
	v_add_u32_e32 v85, 0x4000, v85
	s_nop 4
	v_cndmask_b32_e64 v222, v8, v11, s[40:41]
	v_cndmask_b32_e64 v223, v9, v10, s[40:41]
	v_cndmask_b32_e64 v224, v10, v9, s[40:41]
	v_cndmask_b32_e64 v225, v11, v8, s[40:41]
	v_mul_f32_e32 v222, v222, v226
	v_mul_f32_e32 v223, v223, v226
	v_mul_f32_e32 v224, v224, v226
	v_mul_f32_e32 v225, v225, v226
	v_mul_f32_e32 v222, v80, v222
	v_mul_f32_e32 v223, v81, v223
	v_mul_f32_e32 v224, v82, v224
	v_mul_f32_e32 v225, v84, v225
	v_mul_f32_e32 v31, v222, v222
	v_fmac_f32_e32 v31, v223, v223
	v_fmac_f32_e32 v31, v224, v224
	v_fmac_f32_e32 v31, v225, v225
	v_add_f32_e32 v28, v28, v31
	s_mov_b64 exec, s[38:39]
	ds_write_b32 v78, v222
	ds_write_b32 v78, v223 offset:8
	ds_write_b32 v78, v224 offset:16
	ds_write_b32 v78, v225 offset:24
	s_mov_b64 exec, -1
	v_add_u32_e32 v78, v78, v79
	v_add_u32_e32 v227, 0x600, v29
	v_cvt_f32_i32_e32 v227, v227
	v_mul_f32_e32 v227, v93, v227
	v_mul_f32_e32 v227, 0x3fb8aa3b, v227
	v_exp_f32_e32 v226, v227
	s_waitcnt vmcnt(8)
	v_mfma_f32_16x16x32_f16 v[8:11], v[244:247], v[0:3], 0
	v_mfma_f32_16x16x32_f16 v[8:11], v[248:251], v[4:7], v[8:11]
	global_load_dwordx4 v[244:247], v85, s[70:71]
	global_load_dwordx4 v[248:251], v85, s[70:71] offset:64
	v_add_u32_e32 v85, 0x4000, v85
	s_nop 4
	v_cndmask_b32_e64 v222, v8, v11, s[40:41]
	v_cndmask_b32_e64 v223, v9, v10, s[40:41]
	v_cndmask_b32_e64 v224, v10, v9, s[40:41]
	v_cndmask_b32_e64 v225, v11, v8, s[40:41]
	v_mul_f32_e32 v222, v222, v226
	v_mul_f32_e32 v223, v223, v226
	v_mul_f32_e32 v224, v224, v226
	v_mul_f32_e32 v225, v225, v226
	v_mul_f32_e32 v222, v80, v222
	v_mul_f32_e32 v223, v81, v223
	v_mul_f32_e32 v224, v82, v224
	v_mul_f32_e32 v225, v84, v225
	v_mul_f32_e32 v31, v222, v222
	v_fmac_f32_e32 v31, v223, v223
	v_fmac_f32_e32 v31, v224, v224
	v_fmac_f32_e32 v31, v225, v225
	v_add_f32_e32 v28, v28, v31
	s_mov_b64 exec, s[38:39]
	ds_write_b32 v78, v222
	ds_write_b32 v78, v223 offset:8
	ds_write_b32 v78, v224 offset:16
	ds_write_b32 v78, v225 offset:24
	s_mov_b64 exec, -1
	v_add_u32_e32 v78, v78, v79
	v_add_u32_e32 v227, 0x680, v29
	v_cvt_f32_i32_e32 v227, v227
	v_mul_f32_e32 v227, v93, v227
	v_mul_f32_e32 v227, 0x3fb8aa3b, v227
	v_exp_f32_e32 v226, v227
	s_waitcnt vmcnt(8)
; __device__ __forceinline__ void phase_hyena(KP kp_, int hf){ asm volatile("" : "+s"(kp_)); const Params p=load_params(kp_);
;     ...
;       _Pragma("unroll 8") for (int i=0;i<64;++i){ int tl=wid+8*i;
;         const _Float16* ap=a3+(size_t)(tl*16+n)*64+kg*8;
;         f16x8 a0=*(const f16x8*)ap, a1=*(const f16x8*)(ap+32);
;         f32x4 dd={0.f,0.f,0.f,0.f};
;         dd=__builtin_amdgcn_mfma_f32_16x16x32_f16(a0,bw0,dd,0,0,0);
;         dd=__builtin_amdgcn_mfma_f32_16x16x32_f16(a1,bw1,dd,0,0,0);
;         if (n<4){ float d0=__expf(dsc*(float)(tl*16)); int lag0=tl*16+kg*4;
;           float v0=dd[0]*d0*pj0, v1=dd[1]*d0*pj1, v2=dd[2]*d0*pj2, v3=dd[3]*d0*pj3;
;           if (!side1){ Zf[2*(lag0)+order]=v0; Zf[2*(lag0+1)+order]=v1; Zf[2*(lag0+2)+order]=v2; Zf[2*(lag0+3)+order]=v3; ssl+=v0*v0+v1*v1+v2*v2+v3*v3; }
;           else { if (lag0>=1){ Zf[2*(16384-lag0)+order]=v0; ssl+=v0*v0; }
;             Zf[2*(16384-lag0-1)+order]=v1; Zf[2*(16384-lag0-2)+order]=v2; Zf[2*(16384-lag0-3)+order]=v3; ssl+=v1*v1+v2*v2+v3*v3; } }
	v_mfma_f32_16x16x32_f16 v[8:11], v[12:15], v[0:3], 0
	v_mfma_f32_16x16x32_f16 v[8:11], v[16:19], v[4:7], v[8:11]
	global_load_dwordx4 v[12:15], v85, s[70:71]
	global_load_dwordx4 v[16:19], v85, s[70:71] offset:64
	v_add_u32_e32 v85, 0x4000, v85
	s_nop 4
	v_cndmask_b32_e64 v222, v8, v11, s[40:41]
	v_cndmask_b32_e64 v223, v9, v10, s[40:41]
	v_cndmask_b32_e64 v224, v10, v9, s[40:41]
	v_cndmask_b32_e64 v225, v11, v8, s[40:41]
	v_mul_f32_e32 v222, v222, v226
	v_mul_f32_e32 v223, v223, v226
	v_mul_f32_e32 v224, v224, v226
	v_mul_f32_e32 v225, v225, v226
	v_mul_f32_e32 v222, v80, v222
	v_mul_f32_e32 v223, v81, v223
	v_mul_f32_e32 v224, v82, v224
	v_mul_f32_e32 v225, v84, v225
	v_mul_f32_e32 v31, v222, v222
	v_fmac_f32_e32 v31, v223, v223
	v_fmac_f32_e32 v31, v224, v224
	v_fmac_f32_e32 v31, v225, v225
	v_add_f32_e32 v28, v28, v31
	s_mov_b64 exec, s[38:39]
	ds_write_b32 v78, v222
	ds_write_b32 v78, v223 offset:8
	ds_write_b32 v78, v224 offset:16
	ds_write_b32 v78, v225 offset:24
	s_mov_b64 exec, -1
	v_add_u32_e32 v78, v78, v79
	v_add_u32_e32 v227, 0x700, v29
	v_cvt_f32_i32_e32 v227, v227
	v_mul_f32_e32 v227, v93, v227
	v_mul_f32_e32 v227, 0x3fb8aa3b, v227
	v_exp_f32_e32 v226, v227
	s_waitcnt vmcnt(8)
	v_mfma_f32_16x16x32_f16 v[8:11], v[20:23], v[0:3], 0
	v_mfma_f32_16x16x32_f16 v[8:11], v[24:27], v[4:7], v[8:11]
	global_load_dwordx4 v[20:23], v85, s[70:71]
	global_load_dwordx4 v[24:27], v85, s[70:71] offset:64
	v_add_u32_e32 v85, 0x4000, v85
	s_nop 4
	v_cndmask_b32_e64 v222, v8, v11, s[40:41]
	v_cndmask_b32_e64 v223, v9, v10, s[40:41]
	v_cndmask_b32_e64 v224, v10, v9, s[40:41]
	v_cndmask_b32_e64 v225, v11, v8, s[40:41]
	v_mul_f32_e32 v222, v222, v226
	v_mul_f32_e32 v223, v223, v226
	v_mul_f32_e32 v224, v224, v226
	v_mul_f32_e32 v225, v225, v226
	v_mul_f32_e32 v222, v80, v222
	v_mul_f32_e32 v223, v81, v223
	v_mul_f32_e32 v224, v82, v224
	v_mul_f32_e32 v225, v84, v225
	v_mul_f32_e32 v31, v222, v222
	v_fmac_f32_e32 v31, v223, v223
	v_fmac_f32_e32 v31, v224, v224
	v_fmac_f32_e32 v31, v225, v225
	v_add_f32_e32 v28, v28, v31
	s_mov_b64 exec, s[38:39]
	ds_write_b32 v78, v222
	ds_write_b32 v78, v223 offset:8
	ds_write_b32 v78, v224 offset:16
	ds_write_b32 v78, v225 offset:24
	s_mov_b64 exec, -1
	v_add_u32_e32 v78, v78, v79
	v_add_u32_e32 v227, 0x780, v29
	v_cvt_f32_i32_e32 v227, v227
	v_mul_f32_e32 v227, v93, v227
	v_mul_f32_e32 v227, 0x3fb8aa3b, v227
	v_exp_f32_e32 v226, v227
	s_waitcnt vmcnt(8)
	v_mfma_f32_16x16x32_f16 v[8:11], v[228:231], v[0:3], 0
	v_mfma_f32_16x16x32_f16 v[8:11], v[232:235], v[4:7], v[8:11]
	global_load_dwordx4 v[228:231], v85, s[70:71]
	global_load_dwordx4 v[232:235], v85, s[70:71] offset:64
	v_add_u32_e32 v85, 0x4000, v85
	s_nop 4
	v_cndmask_b32_e64 v222, v8, v11, s[40:41]
	v_cndmask_b32_e64 v223, v9, v10, s[40:41]
	v_cndmask_b32_e64 v224, v10, v9, s[40:41]
	v_cndmask_b32_e64 v225, v11, v8, s[40:41]
	v_mul_f32_e32 v222, v222, v226
	v_mul_f32_e32 v223, v223, v226
	v_mul_f32_e32 v224, v224, v226
	v_mul_f32_e32 v225, v225, v226
	v_mul_f32_e32 v222, v80, v222
	v_mul_f32_e32 v223, v81, v223
	v_mul_f32_e32 v224, v82, v224
	v_mul_f32_e32 v225, v84, v225
	v_mul_f32_e32 v31, v222, v222
	v_fmac_f32_e32 v31, v223, v223
	v_fmac_f32_e32 v31, v224, v224
	v_fmac_f32_e32 v31, v225, v225
	v_add_f32_e32 v28, v28, v31
	s_mov_b64 exec, s[38:39]
	ds_write_b32 v78, v222
	ds_write_b32 v78, v223 offset:8
	ds_write_b32 v78, v224 offset:16
	ds_write_b32 v78, v225 offset:24
	s_mov_b64 exec, -1
	v_add_u32_e32 v78, v78, v79
	v_add_u32_e32 v227, 0x800, v29
	v_cvt_f32_i32_e32 v227, v227
	v_mul_f32_e32 v227, v93, v227
	v_mul_f32_e32 v227, 0x3fb8aa3b, v227
	v_exp_f32_e32 v226, v227
	s_waitcnt vmcnt(8)
	v_mfma_f32_16x16x32_f16 v[8:11], v[236:239], v[0:3], 0
	v_mfma_f32_16x16x32_f16 v[8:11], v[240:243], v[4:7], v[8:11]
	global_load_dwordx4 v[236:239], v85, s[70:71]
	global_load_dwordx4 v[240:243], v85, s[70:71] offset:64
	v_add_u32_e32 v85, 0x4000, v85
	s_nop 4
	v_cndmask_b32_e64 v222, v8, v11, s[40:41]
	v_cndmask_b32_e64 v223, v9, v10, s[40:41]
	v_cndmask_b32_e64 v224, v10, v9, s[40:41]
	v_cndmask_b32_e64 v225, v11, v8, s[40:41]
	v_mul_f32_e32 v222, v222, v226
	v_mul_f32_e32 v223, v223, v226
	v_mul_f32_e32 v224, v224, v226
	v_mul_f32_e32 v225, v225, v226
	v_mul_f32_e32 v222, v80, v222
	v_mul_f32_e32 v223, v81, v223
	v_mul_f32_e32 v224, v82, v224
	v_mul_f32_e32 v225, v84, v225
	v_mul_f32_e32 v31, v222, v222
	v_fmac_f32_e32 v31, v223, v223
	v_fmac_f32_e32 v31, v224, v224
	v_fmac_f32_e32 v31, v225, v225
	v_add_f32_e32 v28, v28, v31
	s_mov_b64 exec, s[38:39]
	ds_write_b32 v78, v222
	ds_write_b32 v78, v223 offset:8
	ds_write_b32 v78, v224 offset:16
	ds_write_b32 v78, v225 offset:24
	s_mov_b64 exec, -1
	v_add_u32_e32 v78, v78, v79
	v_add_u32_e32 v227, 0x880, v29
	v_cvt_f32_i32_e32 v227, v227
	v_mul_f32_e32 v227, v93, v227
	v_mul_f32_e32 v227, 0x3fb8aa3b, v227
	v_exp_f32_e32 v226, v227
	s_waitcnt vmcnt(8)
	v_mfma_f32_16x16x32_f16 v[8:11], v[244:247], v[0:3], 0
	v_mfma_f32_16x16x32_f16 v[8:11], v[248:251], v[4:7], v[8:11]
	global_load_dwordx4 v[244:247], v85, s[70:71]
	global_load_dwordx4 v[248:251], v85, s[70:71] offset:64
	v_add_u32_e32 v85, 0x4000, v85
	s_nop 4
	v_cndmask_b32_e64 v222, v8, v11, s[40:41]
	v_cndmask_b32_e64 v223, v9, v10, s[40:41]
	v_cndmask_b32_e64 v224, v10, v9, s[40:41]
	v_cndmask_b32_e64 v225, v11, v8, s[40:41]
	v_mul_f32_e32 v222, v222, v226
	v_mul_f32_e32 v223, v223, v226
	v_mul_f32_e32 v224, v224, v226
	v_mul_f32_e32 v225, v225, v226
	v_mul_f32_e32 v222, v80, v222
	v_mul_f32_e32 v223, v81, v223
	v_mul_f32_e32 v224, v82, v224
	v_mul_f32_e32 v225, v84, v225
	v_mul_f32_e32 v31, v222, v222
	v_fmac_f32_e32 v31, v223, v223
	v_fmac_f32_e32 v31, v224, v224
	v_fmac_f32_e32 v31, v225, v225
	v_add_f32_e32 v28, v28, v31
	s_mov_b64 exec, s[38:39]
	ds_write_b32 v78, v222
	ds_write_b32 v78, v223 offset:8
	ds_write_b32 v78, v224 offset:16
	ds_write_b32 v78, v225 offset:24
	s_mov_b64 exec, -1
	v_add_u32_e32 v78, v78, v79
	v_add_u32_e32 v227, 0x900, v29
	v_cvt_f32_i32_e32 v227, v227
	v_mul_f32_e32 v227, v93, v227
	v_mul_f32_e32 v227, 0x3fb8aa3b, v227
	v_exp_f32_e32 v226, v227
	s_waitcnt vmcnt(8)
; __device__ __forceinline__ void phase_hyena(KP kp_, int hf){ asm volatile("" : "+s"(kp_)); const Params p=load_params(kp_);
;     ...
;       _Pragma("unroll 8") for (int i=0;i<64;++i){ int tl=wid+8*i;
;         const _Float16* ap=a3+(size_t)(tl*16+n)*64+kg*8;
;         f16x8 a0=*(const f16x8*)ap, a1=*(const f16x8*)(ap+32);
;         f32x4 dd={0.f,0.f,0.f,0.f};
;         dd=__builtin_amdgcn_mfma_f32_16x16x32_f16(a0,bw0,dd,0,0,0);
;         dd=__builtin_amdgcn_mfma_f32_16x16x32_f16(a1,bw1,dd,0,0,0);
;         if (n<4){ float d0=__expf(dsc*(float)(tl*16)); int lag0=tl*16+kg*4;
;           float v0=dd[0]*d0*pj0, v1=dd[1]*d0*pj1, v2=dd[2]*d0*pj2, v3=dd[3]*d0*pj3;
;           if (!side1){ Zf[2*(lag0)+order]=v0; Zf[2*(lag0+1)+order]=v1; Zf[2*(lag0+2)+order]=v2; Zf[2*(lag0+3)+order]=v3; ssl+=v0*v0+v1*v1+v2*v2+v3*v3; }
;           else { if (lag0>=1){ Zf[2*(16384-lag0)+order]=v0; ssl+=v0*v0; }
;             Zf[2*(16384-lag0-1)+order]=v1; Zf[2*(16384-lag0-2)+order]=v2; Zf[2*(16384-lag0-3)+order]=v3; ssl+=v1*v1+v2*v2+v3*v3; } }
	v_mfma_f32_16x16x32_f16 v[8:11], v[12:15], v[0:3], 0
	v_mfma_f32_16x16x32_f16 v[8:11], v[16:19], v[4:7], v[8:11]
	global_load_dwordx4 v[12:15], v85, s[70:71]
	global_load_dwordx4 v[16:19], v85, s[70:71] offset:64
	v_add_u32_e32 v85, 0x4000, v85
	s_nop 4
	v_cndmask_b32_e64 v222, v8, v11, s[40:41]
	v_cndmask_b32_e64 v223, v9, v10, s[40:41]
	v_cndmask_b32_e64 v224, v10, v9, s[40:41]
	v_cndmask_b32_e64 v225, v11, v8, s[40:41]
	v_mul_f32_e32 v222, v222, v226
	v_mul_f32_e32 v223, v223, v226
	v_mul_f32_e32 v224, v224, v226
	v_mul_f32_e32 v225, v225, v226
	v_mul_f32_e32 v222, v80, v222
	v_mul_f32_e32 v223, v81, v223
	v_mul_f32_e32 v224, v82, v224
	v_mul_f32_e32 v225, v84, v225
	v_mul_f32_e32 v31, v222, v222
	v_fmac_f32_e32 v31, v223, v223
	v_fmac_f32_e32 v31, v224, v224
	v_fmac_f32_e32 v31, v225, v225
	v_add_f32_e32 v28, v28, v31
	s_mov_b64 exec, s[38:39]
	ds_write_b32 v78, v222
	ds_write_b32 v78, v223 offset:8
	ds_write_b32 v78, v224 offset:16
	ds_write_b32 v78, v225 offset:24
	s_mov_b64 exec, -1
	v_add_u32_e32 v78, v78, v79
	v_add_u32_e32 v227, 0x980, v29
	v_cvt_f32_i32_e32 v227, v227
	v_mul_f32_e32 v227, v93, v227
	v_mul_f32_e32 v227, 0x3fb8aa3b, v227
	v_exp_f32_e32 v226, v227
	s_waitcnt vmcnt(8)
	v_mfma_f32_16x16x32_f16 v[8:11], v[20:23], v[0:3], 0
	v_mfma_f32_16x16x32_f16 v[8:11], v[24:27], v[4:7], v[8:11]
	global_load_dwordx4 v[20:23], v85, s[70:71]
	global_load_dwordx4 v[24:27], v85, s[70:71] offset:64
	v_add_u32_e32 v85, 0x4000, v85
	s_nop 4
	v_cndmask_b32_e64 v222, v8, v11, s[40:41]
	v_cndmask_b32_e64 v223, v9, v10, s[40:41]
	v_cndmask_b32_e64 v224, v10, v9, s[40:41]
	v_cndmask_b32_e64 v225, v11, v8, s[40:41]
	v_mul_f32_e32 v222, v222, v226
	v_mul_f32_e32 v223, v223, v226
	v_mul_f32_e32 v224, v224, v226
	v_mul_f32_e32 v225, v225, v226
	v_mul_f32_e32 v222, v80, v222
	v_mul_f32_e32 v223, v81, v223
	v_mul_f32_e32 v224, v82, v224
	v_mul_f32_e32 v225, v84, v225
	v_mul_f32_e32 v31, v222, v222
	v_fmac_f32_e32 v31, v223, v223
	v_fmac_f32_e32 v31, v224, v224
	v_fmac_f32_e32 v31, v225, v225
	v_add_f32_e32 v28, v28, v31
	s_mov_b64 exec, s[38:39]
	ds_write_b32 v78, v222
	ds_write_b32 v78, v223 offset:8
	ds_write_b32 v78, v224 offset:16
	ds_write_b32 v78, v225 offset:24
	s_mov_b64 exec, -1
	v_add_u32_e32 v78, v78, v79
	v_add_u32_e32 v227, 0xa00, v29
	v_cvt_f32_i32_e32 v227, v227
	v_mul_f32_e32 v227, v93, v227
	v_mul_f32_e32 v227, 0x3fb8aa3b, v227
	v_exp_f32_e32 v226, v227
	s_waitcnt vmcnt(8)
	v_mfma_f32_16x16x32_f16 v[8:11], v[228:231], v[0:3], 0
	v_mfma_f32_16x16x32_f16 v[8:11], v[232:235], v[4:7], v[8:11]
	global_load_dwordx4 v[228:231], v85, s[70:71]
	global_load_dwordx4 v[232:235], v85, s[70:71] offset:64
	v_add_u32_e32 v85, 0x4000, v85
	s_nop 4
	v_cndmask_b32_e64 v222, v8, v11, s[40:41]
	v_cndmask_b32_e64 v223, v9, v10, s[40:41]
	v_cndmask_b32_e64 v224, v10, v9, s[40:41]
	v_cndmask_b32_e64 v225, v11, v8, s[40:41]
	v_mul_f32_e32 v222, v222, v226
	v_mul_f32_e32 v223, v223, v226
	v_mul_f32_e32 v224, v224, v226
	v_mul_f32_e32 v225, v225, v226
	v_mul_f32_e32 v222, v80, v222
	v_mul_f32_e32 v223, v81, v223
	v_mul_f32_e32 v224, v82, v224
	v_mul_f32_e32 v225, v84, v225
	v_mul_f32_e32 v31, v222, v222
	v_fmac_f32_e32 v31, v223, v223
	v_fmac_f32_e32 v31, v224, v224
	v_fmac_f32_e32 v31, v225, v225
	v_add_f32_e32 v28, v28, v31
	s_mov_b64 exec, s[38:39]
	ds_write_b32 v78, v222
	ds_write_b32 v78, v223 offset:8
	ds_write_b32 v78, v224 offset:16
	ds_write_b32 v78, v225 offset:24
	s_mov_b64 exec, -1
	v_add_u32_e32 v78, v78, v79
	v_add_u32_e32 v227, 0xa80, v29
	v_cvt_f32_i32_e32 v227, v227
	v_mul_f32_e32 v227, v93, v227
	v_mul_f32_e32 v227, 0x3fb8aa3b, v227
	v_exp_f32_e32 v226, v227
	s_waitcnt vmcnt(8)
	v_mfma_f32_16x16x32_f16 v[8:11], v[236:239], v[0:3], 0
	v_mfma_f32_16x16x32_f16 v[8:11], v[240:243], v[4:7], v[8:11]
	global_load_dwordx4 v[236:239], v85, s[70:71]
	global_load_dwordx4 v[240:243], v85, s[70:71] offset:64
	v_add_u32_e32 v85, 0x4000, v85
	s_nop 4
	v_cndmask_b32_e64 v222, v8, v11, s[40:41]
	v_cndmask_b32_e64 v223, v9, v10, s[40:41]
	v_cndmask_b32_e64 v224, v10, v9, s[40:41]
	v_cndmask_b32_e64 v225, v11, v8, s[40:41]
	v_mul_f32_e32 v222, v222, v226
	v_mul_f32_e32 v223, v223, v226
	v_mul_f32_e32 v224, v224, v226
	v_mul_f32_e32 v225, v225, v226
	v_mul_f32_e32 v222, v80, v222
	v_mul_f32_e32 v223, v81, v223
	v_mul_f32_e32 v224, v82, v224
	v_mul_f32_e32 v225, v84, v225
	v_mul_f32_e32 v31, v222, v222
	v_fmac_f32_e32 v31, v223, v223
	v_fmac_f32_e32 v31, v224, v224
	v_fmac_f32_e32 v31, v225, v225
	v_add_f32_e32 v28, v28, v31
	s_mov_b64 exec, s[38:39]
	ds_write_b32 v78, v222
	ds_write_b32 v78, v223 offset:8
	ds_write_b32 v78, v224 offset:16
	ds_write_b32 v78, v225 offset:24
	s_mov_b64 exec, -1
	v_add_u32_e32 v78, v78, v79
	v_add_u32_e32 v227, 0xb00, v29
	v_cvt_f32_i32_e32 v227, v227
	v_mul_f32_e32 v227, v93, v227
	v_mul_f32_e32 v227, 0x3fb8aa3b, v227
	v_exp_f32_e32 v226, v227
	s_waitcnt vmcnt(8)
	v_mfma_f32_16x16x32_f16 v[8:11], v[244:247], v[0:3], 0
	v_mfma_f32_16x16x32_f16 v[8:11], v[248:251], v[4:7], v[8:11]
	global_load_dwordx4 v[244:247], v85, s[70:71]
	global_load_dwordx4 v[248:251], v85, s[70:71] offset:64
	v_add_u32_e32 v85, 0x4000, v85
	s_nop 4
	v_cndmask_b32_e64 v222, v8, v11, s[40:41]
	v_cndmask_b32_e64 v223, v9, v10, s[40:41]
	v_cndmask_b32_e64 v224, v10, v9, s[40:41]
	v_cndmask_b32_e64 v225, v11, v8, s[40:41]
	v_mul_f32_e32 v222, v222, v226
	v_mul_f32_e32 v223, v223, v226
	v_mul_f32_e32 v224, v224, v226
	v_mul_f32_e32 v225, v225, v226
	v_mul_f32_e32 v222, v80, v222
	v_mul_f32_e32 v223, v81, v223
	v_mul_f32_e32 v224, v82, v224
	v_mul_f32_e32 v225, v84, v225
	v_mul_f32_e32 v31, v222, v222
	v_fmac_f32_e32 v31, v223, v223
	v_fmac_f32_e32 v31, v224, v224
	v_fmac_f32_e32 v31, v225, v225
	v_add_f32_e32 v28, v28, v31
	s_mov_b64 exec, s[38:39]
	ds_write_b32 v78, v222
	ds_write_b32 v78, v223 offset:8
	ds_write_b32 v78, v224 offset:16
	ds_write_b32 v78, v225 offset:24
	s_mov_b64 exec, -1
	v_add_u32_e32 v78, v78, v79
	v_add_u32_e32 v227, 0xb80, v29
	v_cvt_f32_i32_e32 v227, v227
	v_mul_f32_e32 v227, v93, v227
	v_mul_f32_e32 v227, 0x3fb8aa3b, v227
	v_exp_f32_e32 v226, v227
	s_waitcnt vmcnt(8)
; __device__ __forceinline__ void phase_hyena(KP kp_, int hf){ asm volatile("" : "+s"(kp_)); const Params p=load_params(kp_);
;     ...
;       _Pragma("unroll 8") for (int i=0;i<64;++i){ int tl=wid+8*i;
;         const _Float16* ap=a3+(size_t)(tl*16+n)*64+kg*8;
;         f16x8 a0=*(const f16x8*)ap, a1=*(const f16x8*)(ap+32);
;         f32x4 dd={0.f,0.f,0.f,0.f};
;         dd=__builtin_amdgcn_mfma_f32_16x16x32_f16(a0,bw0,dd,0,0,0);
;         dd=__builtin_amdgcn_mfma_f32_16x16x32_f16(a1,bw1,dd,0,0,0);
;         if (n<4){ float d0=__expf(dsc*(float)(tl*16)); int lag0=tl*16+kg*4;
;           float v0=dd[0]*d0*pj0, v1=dd[1]*d0*pj1, v2=dd[2]*d0*pj2, v3=dd[3]*d0*pj3;
;           if (!side1){ Zf[2*(lag0)+order]=v0; Zf[2*(lag0+1)+order]=v1; Zf[2*(lag0+2)+order]=v2; Zf[2*(lag0+3)+order]=v3; ssl+=v0*v0+v1*v1+v2*v2+v3*v3; }
;           else { if (lag0>=1){ Zf[2*(16384-lag0)+order]=v0; ssl+=v0*v0; }
;             Zf[2*(16384-lag0-1)+order]=v1; Zf[2*(16384-lag0-2)+order]=v2; Zf[2*(16384-lag0-3)+order]=v3; ssl+=v1*v1+v2*v2+v3*v3; } }
	v_mfma_f32_16x16x32_f16 v[8:11], v[12:15], v[0:3], 0
	v_mfma_f32_16x16x32_f16 v[8:11], v[16:19], v[4:7], v[8:11]
	global_load_dwordx4 v[12:15], v85, s[70:71]
	global_load_dwordx4 v[16:19], v85, s[70:71] offset:64
	v_add_u32_e32 v85, 0x4000, v85
	s_nop 4
	v_cndmask_b32_e64 v222, v8, v11, s[40:41]
	v_cndmask_b32_e64 v223, v9, v10, s[40:41]
	v_cndmask_b32_e64 v224, v10, v9, s[40:41]
	v_cndmask_b32_e64 v225, v11, v8, s[40:41]
	v_mul_f32_e32 v222, v222, v226
	v_mul_f32_e32 v223, v223, v226
	v_mul_f32_e32 v224, v224, v226
	v_mul_f32_e32 v225, v225, v226
	v_mul_f32_e32 v222, v80, v222
	v_mul_f32_e32 v223, v81, v223
	v_mul_f32_e32 v224, v82, v224
	v_mul_f32_e32 v225, v84, v225
	v_mul_f32_e32 v31, v222, v222
	v_fmac_f32_e32 v31, v223, v223
	v_fmac_f32_e32 v31, v224, v224
	v_fmac_f32_e32 v31, v225, v225
	v_add_f32_e32 v28, v28, v31
	s_mov_b64 exec, s[38:39]
	ds_write_b32 v78, v222
	ds_write_b32 v78, v223 offset:8
	ds_write_b32 v78, v224 offset:16
	ds_write_b32 v78, v225 offset:24
	s_mov_b64 exec, -1
	v_add_u32_e32 v78, v78, v79
	v_add_u32_e32 v227, 0xc00, v29
	v_cvt_f32_i32_e32 v227, v227
	v_mul_f32_e32 v227, v93, v227
	v_mul_f32_e32 v227, 0x3fb8aa3b, v227
	v_exp_f32_e32 v226, v227
	s_waitcnt vmcnt(8)
	v_mfma_f32_16x16x32_f16 v[8:11], v[20:23], v[0:3], 0
	v_mfma_f32_16x16x32_f16 v[8:11], v[24:27], v[4:7], v[8:11]
	global_load_dwordx4 v[20:23], v85, s[70:71]
	global_load_dwordx4 v[24:27], v85, s[70:71] offset:64
	v_add_u32_e32 v85, 0x4000, v85
	s_nop 4
	v_cndmask_b32_e64 v222, v8, v11, s[40:41]
	v_cndmask_b32_e64 v223, v9, v10, s[40:41]
	v_cndmask_b32_e64 v224, v10, v9, s[40:41]
	v_cndmask_b32_e64 v225, v11, v8, s[40:41]
	v_mul_f32_e32 v222, v222, v226
	v_mul_f32_e32 v223, v223, v226
	v_mul_f32_e32 v224, v224, v226
	v_mul_f32_e32 v225, v225, v226
	v_mul_f32_e32 v222, v80, v222
	v_mul_f32_e32 v223, v81, v223
	v_mul_f32_e32 v224, v82, v224
	v_mul_f32_e32 v225, v84, v225
	v_mul_f32_e32 v31, v222, v222
	v_fmac_f32_e32 v31, v223, v223
	v_fmac_f32_e32 v31, v224, v224
	v_fmac_f32_e32 v31, v225, v225
	v_add_f32_e32 v28, v28, v31
	s_mov_b64 exec, s[38:39]
	ds_write_b32 v78, v222
	ds_write_b32 v78, v223 offset:8
	ds_write_b32 v78, v224 offset:16
	ds_write_b32 v78, v225 offset:24
	s_mov_b64 exec, -1
	v_add_u32_e32 v78, v78, v79
	v_add_u32_e32 v227, 0xc80, v29
	v_cvt_f32_i32_e32 v227, v227
	v_mul_f32_e32 v227, v93, v227
	v_mul_f32_e32 v227, 0x3fb8aa3b, v227
	v_exp_f32_e32 v226, v227
	s_waitcnt vmcnt(8)
	v_mfma_f32_16x16x32_f16 v[8:11], v[228:231], v[0:3], 0
	v_mfma_f32_16x16x32_f16 v[8:11], v[232:235], v[4:7], v[8:11]
	global_load_dwordx4 v[228:231], v85, s[70:71]
	global_load_dwordx4 v[232:235], v85, s[70:71] offset:64
	v_add_u32_e32 v85, 0x4000, v85
	s_nop 4
	v_cndmask_b32_e64 v222, v8, v11, s[40:41]
	v_cndmask_b32_e64 v223, v9, v10, s[40:41]
	v_cndmask_b32_e64 v224, v10, v9, s[40:41]
	v_cndmask_b32_e64 v225, v11, v8, s[40:41]
	v_mul_f32_e32 v222, v222, v226
	v_mul_f32_e32 v223, v223, v226
	v_mul_f32_e32 v224, v224, v226
	v_mul_f32_e32 v225, v225, v226
	v_mul_f32_e32 v222, v80, v222
	v_mul_f32_e32 v223, v81, v223
	v_mul_f32_e32 v224, v82, v224
	v_mul_f32_e32 v225, v84, v225
	v_mul_f32_e32 v31, v222, v222
	v_fmac_f32_e32 v31, v223, v223
	v_fmac_f32_e32 v31, v224, v224
	v_fmac_f32_e32 v31, v225, v225
	v_add_f32_e32 v28, v28, v31
	s_mov_b64 exec, s[38:39]
	ds_write_b32 v78, v222
	ds_write_b32 v78, v223 offset:8
	ds_write_b32 v78, v224 offset:16
	ds_write_b32 v78, v225 offset:24
	s_mov_b64 exec, -1
	v_add_u32_e32 v78, v78, v79
	v_add_u32_e32 v227, 0xd00, v29
	v_cvt_f32_i32_e32 v227, v227
	v_mul_f32_e32 v227, v93, v227
	v_mul_f32_e32 v227, 0x3fb8aa3b, v227
	v_exp_f32_e32 v226, v227
	s_waitcnt vmcnt(8)
	v_mfma_f32_16x16x32_f16 v[8:11], v[236:239], v[0:3], 0
	v_mfma_f32_16x16x32_f16 v[8:11], v[240:243], v[4:7], v[8:11]
	global_load_dwordx4 v[236:239], v85, s[70:71]
	global_load_dwordx4 v[240:243], v85, s[70:71] offset:64
	v_add_u32_e32 v85, 0x4000, v85
	s_nop 4
	v_cndmask_b32_e64 v222, v8, v11, s[40:41]
	v_cndmask_b32_e64 v223, v9, v10, s[40:41]
	v_cndmask_b32_e64 v224, v10, v9, s[40:41]
	v_cndmask_b32_e64 v225, v11, v8, s[40:41]
	v_mul_f32_e32 v222, v222, v226
	v_mul_f32_e32 v223, v223, v226
	v_mul_f32_e32 v224, v224, v226
	v_mul_f32_e32 v225, v225, v226
	v_mul_f32_e32 v222, v80, v222
	v_mul_f32_e32 v223, v81, v223
	v_mul_f32_e32 v224, v82, v224
	v_mul_f32_e32 v225, v84, v225
	v_mul_f32_e32 v31, v222, v222
	v_fmac_f32_e32 v31, v223, v223
	v_fmac_f32_e32 v31, v224, v224
	v_fmac_f32_e32 v31, v225, v225
	v_add_f32_e32 v28, v28, v31
	s_mov_b64 exec, s[38:39]
	ds_write_b32 v78, v222
	ds_write_b32 v78, v223 offset:8
	ds_write_b32 v78, v224 offset:16
	ds_write_b32 v78, v225 offset:24
	s_mov_b64 exec, -1
	v_add_u32_e32 v78, v78, v79
	v_add_u32_e32 v227, 0xd80, v29
	v_cvt_f32_i32_e32 v227, v227
	v_mul_f32_e32 v227, v93, v227
	v_mul_f32_e32 v227, 0x3fb8aa3b, v227
	v_exp_f32_e32 v226, v227
	s_waitcnt vmcnt(8)
	v_mfma_f32_16x16x32_f16 v[8:11], v[244:247], v[0:3], 0
	v_mfma_f32_16x16x32_f16 v[8:11], v[248:251], v[4:7], v[8:11]
	global_load_dwordx4 v[244:247], v85, s[70:71]
	global_load_dwordx4 v[248:251], v85, s[70:71] offset:64
	v_add_u32_e32 v85, 0x4000, v85
	s_nop 4
	v_cndmask_b32_e64 v222, v8, v11, s[40:41]
	v_cndmask_b32_e64 v223, v9, v10, s[40:41]
	v_cndmask_b32_e64 v224, v10, v9, s[40:41]
	v_cndmask_b32_e64 v225, v11, v8, s[40:41]
	v_mul_f32_e32 v222, v222, v226
	v_mul_f32_e32 v223, v223, v226
	v_mul_f32_e32 v224, v224, v226
	v_mul_f32_e32 v225, v225, v226
	v_mul_f32_e32 v222, v80, v222
	v_mul_f32_e32 v223, v81, v223
	v_mul_f32_e32 v224, v82, v224
	v_mul_f32_e32 v225, v84, v225
	v_mul_f32_e32 v31, v222, v222
	v_fmac_f32_e32 v31, v223, v223
	v_fmac_f32_e32 v31, v224, v224
	v_fmac_f32_e32 v31, v225, v225
	v_add_f32_e32 v28, v28, v31
	s_mov_b64 exec, s[38:39]
	ds_write_b32 v78, v222
	ds_write_b32 v78, v223 offset:8
	ds_write_b32 v78, v224 offset:16
	ds_write_b32 v78, v225 offset:24
	s_mov_b64 exec, -1
	v_add_u32_e32 v78, v78, v79
	v_add_u32_e32 v227, 0xe00, v29
	v_cvt_f32_i32_e32 v227, v227
	v_mul_f32_e32 v227, v93, v227
	v_mul_f32_e32 v227, 0x3fb8aa3b, v227
	v_exp_f32_e32 v226, v227
	s_waitcnt vmcnt(8)
; __device__ __forceinline__ void phase_hyena(KP kp_, int hf){ asm volatile("" : "+s"(kp_)); const Params p=load_params(kp_);
;     ...
;       _Pragma("unroll 8") for (int i=0;i<64;++i){ int tl=wid+8*i;
;         const _Float16* ap=a3+(size_t)(tl*16+n)*64+kg*8;
;         f16x8 a0=*(const f16x8*)ap, a1=*(const f16x8*)(ap+32);
;         f32x4 dd={0.f,0.f,0.f,0.f};
;         dd=__builtin_amdgcn_mfma_f32_16x16x32_f16(a0,bw0,dd,0,0,0);
;         dd=__builtin_amdgcn_mfma_f32_16x16x32_f16(a1,bw1,dd,0,0,0);
;         if (n<4){ float d0=__expf(dsc*(float)(tl*16)); int lag0=tl*16+kg*4;
;           float v0=dd[0]*d0*pj0, v1=dd[1]*d0*pj1, v2=dd[2]*d0*pj2, v3=dd[3]*d0*pj3;
;           if (!side1){ Zf[2*(lag0)+order]=v0; Zf[2*(lag0+1)+order]=v1; Zf[2*(lag0+2)+order]=v2; Zf[2*(lag0+3)+order]=v3; ssl+=v0*v0+v1*v1+v2*v2+v3*v3; }
;           else { if (lag0>=1){ Zf[2*(16384-lag0)+order]=v0; ssl+=v0*v0; }
;             Zf[2*(16384-lag0-1)+order]=v1; Zf[2*(16384-lag0-2)+order]=v2; Zf[2*(16384-lag0-3)+order]=v3; ssl+=v1*v1+v2*v2+v3*v3; } }
	v_mfma_f32_16x16x32_f16 v[8:11], v[12:15], v[0:3], 0
	v_mfma_f32_16x16x32_f16 v[8:11], v[16:19], v[4:7], v[8:11]
	global_load_dwordx4 v[12:15], v85, s[70:71]
	global_load_dwordx4 v[16:19], v85, s[70:71] offset:64
	v_add_u32_e32 v85, 0x4000, v85
	s_nop 4
	v_cndmask_b32_e64 v222, v8, v11, s[40:41]
	v_cndmask_b32_e64 v223, v9, v10, s[40:41]
	v_cndmask_b32_e64 v224, v10, v9, s[40:41]
	v_cndmask_b32_e64 v225, v11, v8, s[40:41]
	v_mul_f32_e32 v222, v222, v226
	v_mul_f32_e32 v223, v223, v226
	v_mul_f32_e32 v224, v224, v226
	v_mul_f32_e32 v225, v225, v226
	v_mul_f32_e32 v222, v80, v222
	v_mul_f32_e32 v223, v81, v223
	v_mul_f32_e32 v224, v82, v224
	v_mul_f32_e32 v225, v84, v225
	v_mul_f32_e32 v31, v222, v222
	v_fmac_f32_e32 v31, v223, v223
	v_fmac_f32_e32 v31, v224, v224
	v_fmac_f32_e32 v31, v225, v225
	v_add_f32_e32 v28, v28, v31
	s_mov_b64 exec, s[38:39]
	ds_write_b32 v78, v222
	ds_write_b32 v78, v223 offset:8
	ds_write_b32 v78, v224 offset:16
	ds_write_b32 v78, v225 offset:24
	s_mov_b64 exec, -1
	v_add_u32_e32 v78, v78, v79
	v_add_u32_e32 v227, 0xe80, v29
	v_cvt_f32_i32_e32 v227, v227
	v_mul_f32_e32 v227, v93, v227
	v_mul_f32_e32 v227, 0x3fb8aa3b, v227
	v_exp_f32_e32 v226, v227
	s_waitcnt vmcnt(8)
	v_mfma_f32_16x16x32_f16 v[8:11], v[20:23], v[0:3], 0
	v_mfma_f32_16x16x32_f16 v[8:11], v[24:27], v[4:7], v[8:11]
	global_load_dwordx4 v[20:23], v85, s[70:71]
	global_load_dwordx4 v[24:27], v85, s[70:71] offset:64
	v_add_u32_e32 v85, 0x4000, v85
	s_nop 4
	v_cndmask_b32_e64 v222, v8, v11, s[40:41]
	v_cndmask_b32_e64 v223, v9, v10, s[40:41]
	v_cndmask_b32_e64 v224, v10, v9, s[40:41]
	v_cndmask_b32_e64 v225, v11, v8, s[40:41]
	v_mul_f32_e32 v222, v222, v226
	v_mul_f32_e32 v223, v223, v226
	v_mul_f32_e32 v224, v224, v226
	v_mul_f32_e32 v225, v225, v226
	v_mul_f32_e32 v222, v80, v222
	v_mul_f32_e32 v223, v81, v223
	v_mul_f32_e32 v224, v82, v224
	v_mul_f32_e32 v225, v84, v225
	v_mul_f32_e32 v31, v222, v222
	v_fmac_f32_e32 v31, v223, v223
	v_fmac_f32_e32 v31, v224, v224
	v_fmac_f32_e32 v31, v225, v225
	v_add_f32_e32 v28, v28, v31
	s_mov_b64 exec, s[38:39]
	ds_write_b32 v78, v222
	ds_write_b32 v78, v223 offset:8
	ds_write_b32 v78, v224 offset:16
	ds_write_b32 v78, v225 offset:24
	s_mov_b64 exec, -1
	v_add_u32_e32 v78, v78, v79
	v_add_u32_e32 v227, 0xf00, v29
	v_cvt_f32_i32_e32 v227, v227
	v_mul_f32_e32 v227, v93, v227
	v_mul_f32_e32 v227, 0x3fb8aa3b, v227
	v_exp_f32_e32 v226, v227
	s_waitcnt vmcnt(8)
	v_mfma_f32_16x16x32_f16 v[8:11], v[228:231], v[0:3], 0
	v_mfma_f32_16x16x32_f16 v[8:11], v[232:235], v[4:7], v[8:11]
	global_load_dwordx4 v[228:231], v85, s[70:71]
	global_load_dwordx4 v[232:235], v85, s[70:71] offset:64
	v_add_u32_e32 v85, 0x4000, v85
	s_nop 4
	v_cndmask_b32_e64 v222, v8, v11, s[40:41]
	v_cndmask_b32_e64 v223, v9, v10, s[40:41]
	v_cndmask_b32_e64 v224, v10, v9, s[40:41]
	v_cndmask_b32_e64 v225, v11, v8, s[40:41]
	v_mul_f32_e32 v222, v222, v226
	v_mul_f32_e32 v223, v223, v226
	v_mul_f32_e32 v224, v224, v226
	v_mul_f32_e32 v225, v225, v226
	v_mul_f32_e32 v222, v80, v222
	v_mul_f32_e32 v223, v81, v223
	v_mul_f32_e32 v224, v82, v224
	v_mul_f32_e32 v225, v84, v225
	v_mul_f32_e32 v31, v222, v222
	v_fmac_f32_e32 v31, v223, v223
	v_fmac_f32_e32 v31, v224, v224
	v_fmac_f32_e32 v31, v225, v225
	v_add_f32_e32 v28, v28, v31
	s_mov_b64 exec, s[38:39]
	ds_write_b32 v78, v222
	ds_write_b32 v78, v223 offset:8
	ds_write_b32 v78, v224 offset:16
	ds_write_b32 v78, v225 offset:24
	s_mov_b64 exec, -1
	v_add_u32_e32 v78, v78, v79
	v_add_u32_e32 v227, 0xf80, v29
	v_cvt_f32_i32_e32 v227, v227
	v_mul_f32_e32 v227, v93, v227
	v_mul_f32_e32 v227, 0x3fb8aa3b, v227
	v_exp_f32_e32 v226, v227
	s_waitcnt vmcnt(8)
	v_mfma_f32_16x16x32_f16 v[8:11], v[236:239], v[0:3], 0
	v_mfma_f32_16x16x32_f16 v[8:11], v[240:243], v[4:7], v[8:11]
	global_load_dwordx4 v[236:239], v85, s[70:71]
	global_load_dwordx4 v[240:243], v85, s[70:71] offset:64
	v_add_u32_e32 v85, 0x4000, v85
	s_nop 4
	v_cndmask_b32_e64 v222, v8, v11, s[40:41]
	v_cndmask_b32_e64 v223, v9, v10, s[40:41]
	v_cndmask_b32_e64 v224, v10, v9, s[40:41]
	v_cndmask_b32_e64 v225, v11, v8, s[40:41]
	v_mul_f32_e32 v222, v222, v226
	v_mul_f32_e32 v223, v223, v226
	v_mul_f32_e32 v224, v224, v226
	v_mul_f32_e32 v225, v225, v226
	v_mul_f32_e32 v222, v80, v222
	v_mul_f32_e32 v223, v81, v223
	v_mul_f32_e32 v224, v82, v224
	v_mul_f32_e32 v225, v84, v225
	v_mul_f32_e32 v31, v222, v222
	v_fmac_f32_e32 v31, v223, v223
	v_fmac_f32_e32 v31, v224, v224
	v_fmac_f32_e32 v31, v225, v225
	v_add_f32_e32 v28, v28, v31
	s_mov_b64 exec, s[38:39]
	ds_write_b32 v78, v222
	ds_write_b32 v78, v223 offset:8
	ds_write_b32 v78, v224 offset:16
	ds_write_b32 v78, v225 offset:24
	s_mov_b64 exec, -1
	v_add_u32_e32 v78, v78, v79
	v_add_u32_e32 v227, 0x1000, v29
	v_cvt_f32_i32_e32 v227, v227
	v_mul_f32_e32 v227, v93, v227
	v_mul_f32_e32 v227, 0x3fb8aa3b, v227
	v_exp_f32_e32 v226, v227
	s_waitcnt vmcnt(8)
	v_mfma_f32_16x16x32_f16 v[8:11], v[244:247], v[0:3], 0
	v_mfma_f32_16x16x32_f16 v[8:11], v[248:251], v[4:7], v[8:11]
	global_load_dwordx4 v[244:247], v85, s[70:71]
	global_load_dwordx4 v[248:251], v85, s[70:71] offset:64
	v_add_u32_e32 v85, 0x4000, v85
	s_nop 4
	v_cndmask_b32_e64 v222, v8, v11, s[40:41]
	v_cndmask_b32_e64 v223, v9, v10, s[40:41]
	v_cndmask_b32_e64 v224, v10, v9, s[40:41]
	v_cndmask_b32_e64 v225, v11, v8, s[40:41]
	v_mul_f32_e32 v222, v222, v226
	v_mul_f32_e32 v223, v223, v226
	v_mul_f32_e32 v224, v224, v226
	v_mul_f32_e32 v225, v225, v226
	v_mul_f32_e32 v222, v80, v222
	v_mul_f32_e32 v223, v81, v223
	v_mul_f32_e32 v224, v82, v224
	v_mul_f32_e32 v225, v84, v225
	v_mul_f32_e32 v31, v222, v222
	v_fmac_f32_e32 v31, v223, v223
	v_fmac_f32_e32 v31, v224, v224
	v_fmac_f32_e32 v31, v225, v225
	v_add_f32_e32 v28, v28, v31
	s_mov_b64 exec, s[38:39]
	ds_write_b32 v78, v222
	ds_write_b32 v78, v223 offset:8
	ds_write_b32 v78, v224 offset:16
	ds_write_b32 v78, v225 offset:24
	s_mov_b64 exec, -1
	v_add_u32_e32 v78, v78, v79
	v_add_u32_e32 v227, 0x1080, v29
	v_cvt_f32_i32_e32 v227, v227
	v_mul_f32_e32 v227, v93, v227
	v_mul_f32_e32 v227, 0x3fb8aa3b, v227
	v_exp_f32_e32 v226, v227
	s_waitcnt vmcnt(8)
; __device__ __forceinline__ void phase_hyena(KP kp_, int hf){ asm volatile("" : "+s"(kp_)); const Params p=load_params(kp_);
;     ...
;       _Pragma("unroll 8") for (int i=0;i<64;++i){ int tl=wid+8*i;
;         const _Float16* ap=a3+(size_t)(tl*16+n)*64+kg*8;
;         f16x8 a0=*(const f16x8*)ap, a1=*(const f16x8*)(ap+32);
;         f32x4 dd={0.f,0.f,0.f,0.f};
;         dd=__builtin_amdgcn_mfma_f32_16x16x32_f16(a0,bw0,dd,0,0,0);
;         dd=__builtin_amdgcn_mfma_f32_16x16x32_f16(a1,bw1,dd,0,0,0);
;         if (n<4){ float d0=__expf(dsc*(float)(tl*16)); int lag0=tl*16+kg*4;
;           float v0=dd[0]*d0*pj0, v1=dd[1]*d0*pj1, v2=dd[2]*d0*pj2, v3=dd[3]*d0*pj3;
;           if (!side1){ Zf[2*(lag0)+order]=v0; Zf[2*(lag0+1)+order]=v1; Zf[2*(lag0+2)+order]=v2; Zf[2*(lag0+3)+order]=v3; ssl+=v0*v0+v1*v1+v2*v2+v3*v3; }
;           else { if (lag0>=1){ Zf[2*(16384-lag0)+order]=v0; ssl+=v0*v0; }
;             Zf[2*(16384-lag0-1)+order]=v1; Zf[2*(16384-lag0-2)+order]=v2; Zf[2*(16384-lag0-3)+order]=v3; ssl+=v1*v1+v2*v2+v3*v3; } }
	v_mfma_f32_16x16x32_f16 v[8:11], v[12:15], v[0:3], 0
	v_mfma_f32_16x16x32_f16 v[8:11], v[16:19], v[4:7], v[8:11]
	global_load_dwordx4 v[12:15], v85, s[70:71]
	global_load_dwordx4 v[16:19], v85, s[70:71] offset:64
	v_add_u32_e32 v85, 0x4000, v85
	s_nop 4
	v_cndmask_b32_e64 v222, v8, v11, s[40:41]
	v_cndmask_b32_e64 v223, v9, v10, s[40:41]
	v_cndmask_b32_e64 v224, v10, v9, s[40:41]
	v_cndmask_b32_e64 v225, v11, v8, s[40:41]
	v_mul_f32_e32 v222, v222, v226
	v_mul_f32_e32 v223, v223, v226
	v_mul_f32_e32 v224, v224, v226
	v_mul_f32_e32 v225, v225, v226
	v_mul_f32_e32 v222, v80, v222
	v_mul_f32_e32 v223, v81, v223
	v_mul_f32_e32 v224, v82, v224
	v_mul_f32_e32 v225, v84, v225
	v_mul_f32_e32 v31, v222, v222
	v_fmac_f32_e32 v31, v223, v223
	v_fmac_f32_e32 v31, v224, v224
	v_fmac_f32_e32 v31, v225, v225
	v_add_f32_e32 v28, v28, v31
	s_mov_b64 exec, s[38:39]
	ds_write_b32 v78, v222
	ds_write_b32 v78, v223 offset:8
	ds_write_b32 v78, v224 offset:16
	ds_write_b32 v78, v225 offset:24
	s_mov_b64 exec, -1
	v_add_u32_e32 v78, v78, v79
	v_add_u32_e32 v227, 0x1100, v29
	v_cvt_f32_i32_e32 v227, v227
	v_mul_f32_e32 v227, v93, v227
	v_mul_f32_e32 v227, 0x3fb8aa3b, v227
	v_exp_f32_e32 v226, v227
	s_waitcnt vmcnt(8)
	v_mfma_f32_16x16x32_f16 v[8:11], v[20:23], v[0:3], 0
	v_mfma_f32_16x16x32_f16 v[8:11], v[24:27], v[4:7], v[8:11]
	global_load_dwordx4 v[20:23], v85, s[70:71]
	global_load_dwordx4 v[24:27], v85, s[70:71] offset:64
	v_add_u32_e32 v85, 0x4000, v85
	s_nop 4
	v_cndmask_b32_e64 v222, v8, v11, s[40:41]
	v_cndmask_b32_e64 v223, v9, v10, s[40:41]
	v_cndmask_b32_e64 v224, v10, v9, s[40:41]
	v_cndmask_b32_e64 v225, v11, v8, s[40:41]
	v_mul_f32_e32 v222, v222, v226
	v_mul_f32_e32 v223, v223, v226
	v_mul_f32_e32 v224, v224, v226
	v_mul_f32_e32 v225, v225, v226
	v_mul_f32_e32 v222, v80, v222
	v_mul_f32_e32 v223, v81, v223
	v_mul_f32_e32 v224, v82, v224
	v_mul_f32_e32 v225, v84, v225
	v_mul_f32_e32 v31, v222, v222
	v_fmac_f32_e32 v31, v223, v223
	v_fmac_f32_e32 v31, v224, v224
	v_fmac_f32_e32 v31, v225, v225
	v_add_f32_e32 v28, v28, v31
	s_mov_b64 exec, s[38:39]
	ds_write_b32 v78, v222
	ds_write_b32 v78, v223 offset:8
	ds_write_b32 v78, v224 offset:16
	ds_write_b32 v78, v225 offset:24
	s_mov_b64 exec, -1
	v_add_u32_e32 v78, v78, v79
	v_add_u32_e32 v227, 0x1180, v29
	v_cvt_f32_i32_e32 v227, v227
	v_mul_f32_e32 v227, v93, v227
	v_mul_f32_e32 v227, 0x3fb8aa3b, v227
	v_exp_f32_e32 v226, v227
	s_waitcnt vmcnt(8)
	v_mfma_f32_16x16x32_f16 v[8:11], v[228:231], v[0:3], 0
	v_mfma_f32_16x16x32_f16 v[8:11], v[232:235], v[4:7], v[8:11]
	global_load_dwordx4 v[228:231], v85, s[70:71]
	global_load_dwordx4 v[232:235], v85, s[70:71] offset:64
	v_add_u32_e32 v85, 0x4000, v85
	s_nop 4
	v_cndmask_b32_e64 v222, v8, v11, s[40:41]
	v_cndmask_b32_e64 v223, v9, v10, s[40:41]
	v_cndmask_b32_e64 v224, v10, v9, s[40:41]
	v_cndmask_b32_e64 v225, v11, v8, s[40:41]
	v_mul_f32_e32 v222, v222, v226
	v_mul_f32_e32 v223, v223, v226
	v_mul_f32_e32 v224, v224, v226
	v_mul_f32_e32 v225, v225, v226
	v_mul_f32_e32 v222, v80, v222
	v_mul_f32_e32 v223, v81, v223
	v_mul_f32_e32 v224, v82, v224
	v_mul_f32_e32 v225, v84, v225
	v_mul_f32_e32 v31, v222, v222
	v_fmac_f32_e32 v31, v223, v223
	v_fmac_f32_e32 v31, v224, v224
	v_fmac_f32_e32 v31, v225, v225
	v_add_f32_e32 v28, v28, v31
	s_mov_b64 exec, s[38:39]
	ds_write_b32 v78, v222
	ds_write_b32 v78, v223 offset:8
	ds_write_b32 v78, v224 offset:16
	ds_write_b32 v78, v225 offset:24
	s_mov_b64 exec, -1
	v_add_u32_e32 v78, v78, v79
	v_add_u32_e32 v227, 0x1200, v29
	v_cvt_f32_i32_e32 v227, v227
	v_mul_f32_e32 v227, v93, v227
	v_mul_f32_e32 v227, 0x3fb8aa3b, v227
	v_exp_f32_e32 v226, v227
	s_waitcnt vmcnt(8)
	v_mfma_f32_16x16x32_f16 v[8:11], v[236:239], v[0:3], 0
	v_mfma_f32_16x16x32_f16 v[8:11], v[240:243], v[4:7], v[8:11]
	global_load_dwordx4 v[236:239], v85, s[70:71]
	global_load_dwordx4 v[240:243], v85, s[70:71] offset:64
	v_add_u32_e32 v85, 0x4000, v85
	s_nop 4
	v_cndmask_b32_e64 v222, v8, v11, s[40:41]
	v_cndmask_b32_e64 v223, v9, v10, s[40:41]
	v_cndmask_b32_e64 v224, v10, v9, s[40:41]
	v_cndmask_b32_e64 v225, v11, v8, s[40:41]
	v_mul_f32_e32 v222, v222, v226
	v_mul_f32_e32 v223, v223, v226
	v_mul_f32_e32 v224, v224, v226
	v_mul_f32_e32 v225, v225, v226
	v_mul_f32_e32 v222, v80, v222
	v_mul_f32_e32 v223, v81, v223
	v_mul_f32_e32 v224, v82, v224
	v_mul_f32_e32 v225, v84, v225
	v_mul_f32_e32 v31, v222, v222
	v_fmac_f32_e32 v31, v223, v223
	v_fmac_f32_e32 v31, v224, v224
	v_fmac_f32_e32 v31, v225, v225
	v_add_f32_e32 v28, v28, v31
	s_mov_b64 exec, s[38:39]
	ds_write_b32 v78, v222
	ds_write_b32 v78, v223 offset:8
	ds_write_b32 v78, v224 offset:16
	ds_write_b32 v78, v225 offset:24
	s_mov_b64 exec, -1
	v_add_u32_e32 v78, v78, v79
	v_add_u32_e32 v227, 0x1280, v29
	v_cvt_f32_i32_e32 v227, v227
	v_mul_f32_e32 v227, v93, v227
	v_mul_f32_e32 v227, 0x3fb8aa3b, v227
	v_exp_f32_e32 v226, v227
	s_waitcnt vmcnt(8)
	v_mfma_f32_16x16x32_f16 v[8:11], v[244:247], v[0:3], 0
	v_mfma_f32_16x16x32_f16 v[8:11], v[248:251], v[4:7], v[8:11]
	global_load_dwordx4 v[244:247], v85, s[70:71]
	global_load_dwordx4 v[248:251], v85, s[70:71] offset:64
	v_add_u32_e32 v85, 0x4000, v85
	s_nop 4
	v_cndmask_b32_e64 v222, v8, v11, s[40:41]
	v_cndmask_b32_e64 v223, v9, v10, s[40:41]
	v_cndmask_b32_e64 v224, v10, v9, s[40:41]
	v_cndmask_b32_e64 v225, v11, v8, s[40:41]
	v_mul_f32_e32 v222, v222, v226
	v_mul_f32_e32 v223, v223, v226
	v_mul_f32_e32 v224, v224, v226
	v_mul_f32_e32 v225, v225, v226
	v_mul_f32_e32 v222, v80, v222
	v_mul_f32_e32 v223, v81, v223
	v_mul_f32_e32 v224, v82, v224
	v_mul_f32_e32 v225, v84, v225
	v_mul_f32_e32 v31, v222, v222
	v_fmac_f32_e32 v31, v223, v223
	v_fmac_f32_e32 v31, v224, v224
	v_fmac_f32_e32 v31, v225, v225
	v_add_f32_e32 v28, v28, v31
	s_mov_b64 exec, s[38:39]
	ds_write_b32 v78, v222
	ds_write_b32 v78, v223 offset:8
	ds_write_b32 v78, v224 offset:16
	ds_write_b32 v78, v225 offset:24
	s_mov_b64 exec, -1
	v_add_u32_e32 v78, v78, v79
	v_add_u32_e32 v227, 0x1300, v29
	v_cvt_f32_i32_e32 v227, v227
	v_mul_f32_e32 v227, v93, v227
	v_mul_f32_e32 v227, 0x3fb8aa3b, v227
	v_exp_f32_e32 v226, v227
	s_waitcnt vmcnt(8)
; __device__ __forceinline__ void phase_hyena(KP kp_, int hf){ asm volatile("" : "+s"(kp_)); const Params p=load_params(kp_);
;     ...
;       _Pragma("unroll 8") for (int i=0;i<64;++i){ int tl=wid+8*i;
;         const _Float16* ap=a3+(size_t)(tl*16+n)*64+kg*8;
;         f16x8 a0=*(const f16x8*)ap, a1=*(const f16x8*)(ap+32);
;         f32x4 dd={0.f,0.f,0.f,0.f};
;         dd=__builtin_amdgcn_mfma_f32_16x16x32_f16(a0,bw0,dd,0,0,0);
;         dd=__builtin_amdgcn_mfma_f32_16x16x32_f16(a1,bw1,dd,0,0,0);
;         if (n<4){ float d0=__expf(dsc*(float)(tl*16)); int lag0=tl*16+kg*4;
;           float v0=dd[0]*d0*pj0, v1=dd[1]*d0*pj1, v2=dd[2]*d0*pj2, v3=dd[3]*d0*pj3;
;           if (!side1){ Zf[2*(lag0)+order]=v0; Zf[2*(lag0+1)+order]=v1; Zf[2*(lag0+2)+order]=v2; Zf[2*(lag0+3)+order]=v3; ssl+=v0*v0+v1*v1+v2*v2+v3*v3; }
;           else { if (lag0>=1){ Zf[2*(16384-lag0)+order]=v0; ssl+=v0*v0; }
;             Zf[2*(16384-lag0-1)+order]=v1; Zf[2*(16384-lag0-2)+order]=v2; Zf[2*(16384-lag0-3)+order]=v3; ssl+=v1*v1+v2*v2+v3*v3; } }
;       }
	v_mfma_f32_16x16x32_f16 v[8:11], v[12:15], v[0:3], 0
	v_mfma_f32_16x16x32_f16 v[8:11], v[16:19], v[4:7], v[8:11]
	global_load_dwordx4 v[12:15], v85, s[70:71]
	global_load_dwordx4 v[16:19], v85, s[70:71] offset:64
	v_add_u32_e32 v85, 0x4000, v85
	s_nop 4
	v_cndmask_b32_e64 v222, v8, v11, s[40:41]
	v_cndmask_b32_e64 v223, v9, v10, s[40:41]
	v_cndmask_b32_e64 v224, v10, v9, s[40:41]
	v_cndmask_b32_e64 v225, v11, v8, s[40:41]
	v_mul_f32_e32 v222, v222, v226
	v_mul_f32_e32 v223, v223, v226
	v_mul_f32_e32 v224, v224, v226
	v_mul_f32_e32 v225, v225, v226
	v_mul_f32_e32 v222, v80, v222
	v_mul_f32_e32 v223, v81, v223
	v_mul_f32_e32 v224, v82, v224
	v_mul_f32_e32 v225, v84, v225
	v_mul_f32_e32 v31, v222, v222
	v_fmac_f32_e32 v31, v223, v223
	v_fmac_f32_e32 v31, v224, v224
	v_fmac_f32_e32 v31, v225, v225
	v_add_f32_e32 v28, v28, v31
	s_mov_b64 exec, s[38:39]
	ds_write_b32 v78, v222
	ds_write_b32 v78, v223 offset:8
	ds_write_b32 v78, v224 offset:16
	ds_write_b32 v78, v225 offset:24
	s_mov_b64 exec, -1
	v_add_u32_e32 v78, v78, v79
	v_add_u32_e32 v227, 0x1380, v29
	v_cvt_f32_i32_e32 v227, v227
	v_mul_f32_e32 v227, v93, v227
	v_mul_f32_e32 v227, 0x3fb8aa3b, v227
	v_exp_f32_e32 v226, v227
	s_waitcnt vmcnt(8)
	v_mfma_f32_16x16x32_f16 v[8:11], v[20:23], v[0:3], 0
	v_mfma_f32_16x16x32_f16 v[8:11], v[24:27], v[4:7], v[8:11]
	global_load_dwordx4 v[20:23], v85, s[70:71]
	global_load_dwordx4 v[24:27], v85, s[70:71] offset:64
	v_add_u32_e32 v85, 0x4000, v85
	s_nop 4
	v_cndmask_b32_e64 v222, v8, v11, s[40:41]
	v_cndmask_b32_e64 v223, v9, v10, s[40:41]
	v_cndmask_b32_e64 v224, v10, v9, s[40:41]
	v_cndmask_b32_e64 v225, v11, v8, s[40:41]
	v_mul_f32_e32 v222, v222, v226
	v_mul_f32_e32 v223, v223, v226
	v_mul_f32_e32 v224, v224, v226
	v_mul_f32_e32 v225, v225, v226
	v_mul_f32_e32 v222, v80, v222
	v_mul_f32_e32 v223, v81, v223
	v_mul_f32_e32 v224, v82, v224
	v_mul_f32_e32 v225, v84, v225
	v_mul_f32_e32 v31, v222, v222
	v_fmac_f32_e32 v31, v223, v223
	v_fmac_f32_e32 v31, v224, v224
	v_fmac_f32_e32 v31, v225, v225
	v_add_f32_e32 v28, v28, v31
	s_mov_b64 exec, s[38:39]
	ds_write_b32 v78, v222
	ds_write_b32 v78, v223 offset:8
	ds_write_b32 v78, v224 offset:16
	ds_write_b32 v78, v225 offset:24
	s_mov_b64 exec, -1
	v_add_u32_e32 v78, v78, v79
	v_add_u32_e32 v227, 0x1400, v29
	v_cvt_f32_i32_e32 v227, v227
	v_mul_f32_e32 v227, v93, v227
	v_mul_f32_e32 v227, 0x3fb8aa3b, v227
	v_exp_f32_e32 v226, v227
	s_waitcnt vmcnt(8)
	v_mfma_f32_16x16x32_f16 v[8:11], v[228:231], v[0:3], 0
	v_mfma_f32_16x16x32_f16 v[8:11], v[232:235], v[4:7], v[8:11]
	global_load_dwordx4 v[228:231], v85, s[70:71]
	global_load_dwordx4 v[232:235], v85, s[70:71] offset:64
	v_add_u32_e32 v85, 0x4000, v85
	s_nop 4
	v_cndmask_b32_e64 v222, v8, v11, s[40:41]
	v_cndmask_b32_e64 v223, v9, v10, s[40:41]
	v_cndmask_b32_e64 v224, v10, v9, s[40:41]
	v_cndmask_b32_e64 v225, v11, v8, s[40:41]
	v_mul_f32_e32 v222, v222, v226
	v_mul_f32_e32 v223, v223, v226
	v_mul_f32_e32 v224, v224, v226
	v_mul_f32_e32 v225, v225, v226
	v_mul_f32_e32 v222, v80, v222
	v_mul_f32_e32 v223, v81, v223
	v_mul_f32_e32 v224, v82, v224
	v_mul_f32_e32 v225, v84, v225
	v_mul_f32_e32 v31, v222, v222
	v_fmac_f32_e32 v31, v223, v223
	v_fmac_f32_e32 v31, v224, v224
	v_fmac_f32_e32 v31, v225, v225
	v_add_f32_e32 v28, v28, v31
	s_mov_b64 exec, s[38:39]
	ds_write_b32 v78, v222
	ds_write_b32 v78, v223 offset:8
	ds_write_b32 v78, v224 offset:16
	ds_write_b32 v78, v225 offset:24
	s_mov_b64 exec, -1
	v_add_u32_e32 v78, v78, v79
	v_add_u32_e32 v227, 0x1480, v29
	v_cvt_f32_i32_e32 v227, v227
	v_mul_f32_e32 v227, v93, v227
	v_mul_f32_e32 v227, 0x3fb8aa3b, v227
	v_exp_f32_e32 v226, v227
	s_waitcnt vmcnt(8)
	v_mfma_f32_16x16x32_f16 v[8:11], v[236:239], v[0:3], 0
	v_mfma_f32_16x16x32_f16 v[8:11], v[240:243], v[4:7], v[8:11]
	global_load_dwordx4 v[236:239], v85, s[70:71]
	global_load_dwordx4 v[240:243], v85, s[70:71] offset:64
	v_add_u32_e32 v85, 0x4000, v85
	s_nop 4
	v_cndmask_b32_e64 v222, v8, v11, s[40:41]
	v_cndmask_b32_e64 v223, v9, v10, s[40:41]
	v_cndmask_b32_e64 v224, v10, v9, s[40:41]
	v_cndmask_b32_e64 v225, v11, v8, s[40:41]
	v_mul_f32_e32 v222, v222, v226
	v_mul_f32_e32 v223, v223, v226
	v_mul_f32_e32 v224, v224, v226
	v_mul_f32_e32 v225, v225, v226
	v_mul_f32_e32 v222, v80, v222
	v_mul_f32_e32 v223, v81, v223
	v_mul_f32_e32 v224, v82, v224
	v_mul_f32_e32 v225, v84, v225
	v_mul_f32_e32 v31, v222, v222
	v_fmac_f32_e32 v31, v223, v223
	v_fmac_f32_e32 v31, v224, v224
	v_fmac_f32_e32 v31, v225, v225
	v_add_f32_e32 v28, v28, v31
	s_mov_b64 exec, s[38:39]
	ds_write_b32 v78, v222
	ds_write_b32 v78, v223 offset:8
	ds_write_b32 v78, v224 offset:16
	ds_write_b32 v78, v225 offset:24
	s_mov_b64 exec, -1
	v_add_u32_e32 v78, v78, v79
	v_add_u32_e32 v227, 0x1500, v29
	v_cvt_f32_i32_e32 v227, v227
	v_mul_f32_e32 v227, v93, v227
	v_mul_f32_e32 v227, 0x3fb8aa3b, v227
	v_exp_f32_e32 v226, v227
	s_waitcnt vmcnt(8)
	v_mfma_f32_16x16x32_f16 v[8:11], v[244:247], v[0:3], 0
	v_mfma_f32_16x16x32_f16 v[8:11], v[248:251], v[4:7], v[8:11]
	global_load_dwordx4 v[244:247], v85, s[70:71]
	global_load_dwordx4 v[248:251], v85, s[70:71] offset:64
	v_add_u32_e32 v85, 0x4000, v85
	s_nop 4
	v_cndmask_b32_e64 v222, v8, v11, s[40:41]
	v_cndmask_b32_e64 v223, v9, v10, s[40:41]
	v_cndmask_b32_e64 v224, v10, v9, s[40:41]
	v_cndmask_b32_e64 v225, v11, v8, s[40:41]
	v_mul_f32_e32 v222, v222, v226
	v_mul_f32_e32 v223, v223, v226
	v_mul_f32_e32 v224, v224, v226
	v_mul_f32_e32 v225, v225, v226
	v_mul_f32_e32 v222, v80, v222
	v_mul_f32_e32 v223, v81, v223
	v_mul_f32_e32 v224, v82, v224
	v_mul_f32_e32 v225, v84, v225
	v_mul_f32_e32 v31, v222, v222
	v_fmac_f32_e32 v31, v223, v223
	v_fmac_f32_e32 v31, v224, v224
	v_fmac_f32_e32 v31, v225, v225
	v_add_f32_e32 v28, v28, v31
	s_mov_b64 exec, s[38:39]
	ds_write_b32 v78, v222
	ds_write_b32 v78, v223 offset:8
	ds_write_b32 v78, v224 offset:16
	ds_write_b32 v78, v225 offset:24
	s_mov_b64 exec, -1
	v_add_u32_e32 v78, v78, v79
	v_add_u32_e32 v227, 0x1580, v29
	v_cvt_f32_i32_e32 v227, v227
	v_mul_f32_e32 v227, v93, v227
	v_mul_f32_e32 v227, 0x3fb8aa3b, v227
	v_exp_f32_e32 v226, v227
	s_waitcnt vmcnt(8)
; __device__ __forceinline__ void phase_hyena(KP kp_, int hf){ asm volatile("" : "+s"(kp_)); const Params p=load_params(kp_);
;     ...
;       _Pragma("unroll 8") for (int i=0;i<64;++i){ int tl=wid+8*i;
;         const _Float16* ap=a3+(size_t)(tl*16+n)*64+kg*8;
;         f16x8 a0=*(const f16x8*)ap, a1=*(const f16x8*)(ap+32);
;         f32x4 dd={0.f,0.f,0.f,0.f};
;         dd=__builtin_amdgcn_mfma_f32_16x16x32_f16(a0,bw0,dd,0,0,0);
;         dd=__builtin_amdgcn_mfma_f32_16x16x32_f16(a1,bw1,dd,0,0,0);
;         if (n<4){ float d0=__expf(dsc*(float)(tl*16)); int lag0=tl*16+kg*4;
;           float v0=dd[0]*d0*pj0, v1=dd[1]*d0*pj1, v2=dd[2]*d0*pj2, v3=dd[3]*d0*pj3;
;           if (!side1){ Zf[2*(lag0)+order]=v0; Zf[2*(lag0+1)+order]=v1; Zf[2*(lag0+2)+order]=v2; Zf[2*(lag0+3)+order]=v3; ssl+=v0*v0+v1*v1+v2*v2+v3*v3; }
;           else { if (lag0>=1){ Zf[2*(16384-lag0)+order]=v0; ssl+=v0*v0; }
;             Zf[2*(16384-lag0-1)+order]=v1; Zf[2*(16384-lag0-2)+order]=v2; Zf[2*(16384-lag0-3)+order]=v3; ssl+=v1*v1+v2*v2+v3*v3; } }
;       }
	v_mfma_f32_16x16x32_f16 v[8:11], v[12:15], v[0:3], 0
	v_mfma_f32_16x16x32_f16 v[8:11], v[16:19], v[4:7], v[8:11]
	global_load_dwordx4 v[12:15], v85, s[70:71]
	global_load_dwordx4 v[16:19], v85, s[70:71] offset:64
	v_add_u32_e32 v85, 0x4000, v85
	s_nop 4
	v_cndmask_b32_e64 v222, v8, v11, s[40:41]
	v_cndmask_b32_e64 v223, v9, v10, s[40:41]
	v_cndmask_b32_e64 v224, v10, v9, s[40:41]
	v_cndmask_b32_e64 v225, v11, v8, s[40:41]
	v_mul_f32_e32 v222, v222, v226
	v_mul_f32_e32 v223, v223, v226
	v_mul_f32_e32 v224, v224, v226
	v_mul_f32_e32 v225, v225, v226
	v_mul_f32_e32 v222, v80, v222
	v_mul_f32_e32 v223, v81, v223
	v_mul_f32_e32 v224, v82, v224
	v_mul_f32_e32 v225, v84, v225
	v_mul_f32_e32 v31, v222, v222
	v_fmac_f32_e32 v31, v223, v223
	v_fmac_f32_e32 v31, v224, v224
	v_fmac_f32_e32 v31, v225, v225
	v_add_f32_e32 v28, v28, v31
	s_mov_b64 exec, s[38:39]
	ds_write_b32 v78, v222
	ds_write_b32 v78, v223 offset:8
	ds_write_b32 v78, v224 offset:16
	ds_write_b32 v78, v225 offset:24
	s_mov_b64 exec, -1
	v_add_u32_e32 v78, v78, v79
	v_add_u32_e32 v227, 0x1600, v29
	v_cvt_f32_i32_e32 v227, v227
	v_mul_f32_e32 v227, v93, v227
	v_mul_f32_e32 v227, 0x3fb8aa3b, v227
	v_exp_f32_e32 v226, v227
	s_waitcnt vmcnt(8)
	v_mfma_f32_16x16x32_f16 v[8:11], v[20:23], v[0:3], 0
	v_mfma_f32_16x16x32_f16 v[8:11], v[24:27], v[4:7], v[8:11]
	global_load_dwordx4 v[20:23], v85, s[70:71]
	global_load_dwordx4 v[24:27], v85, s[70:71] offset:64
	v_add_u32_e32 v85, 0x4000, v85
	s_nop 4
	v_cndmask_b32_e64 v222, v8, v11, s[40:41]
	v_cndmask_b32_e64 v223, v9, v10, s[40:41]
	v_cndmask_b32_e64 v224, v10, v9, s[40:41]
	v_cndmask_b32_e64 v225, v11, v8, s[40:41]
	v_mul_f32_e32 v222, v222, v226
	v_mul_f32_e32 v223, v223, v226
	v_mul_f32_e32 v224, v224, v226
	v_mul_f32_e32 v225, v225, v226
	v_mul_f32_e32 v222, v80, v222
	v_mul_f32_e32 v223, v81, v223
	v_mul_f32_e32 v224, v82, v224
	v_mul_f32_e32 v225, v84, v225
	v_mul_f32_e32 v31, v222, v222
	v_fmac_f32_e32 v31, v223, v223
	v_fmac_f32_e32 v31, v224, v224
	v_fmac_f32_e32 v31, v225, v225
	v_add_f32_e32 v28, v28, v31
	s_mov_b64 exec, s[38:39]
	ds_write_b32 v78, v222
	ds_write_b32 v78, v223 offset:8
	ds_write_b32 v78, v224 offset:16
	ds_write_b32 v78, v225 offset:24
	s_mov_b64 exec, -1
	v_add_u32_e32 v78, v78, v79
	v_add_u32_e32 v227, 0x1680, v29
	v_cvt_f32_i32_e32 v227, v227
	v_mul_f32_e32 v227, v93, v227
	v_mul_f32_e32 v227, 0x3fb8aa3b, v227
	v_exp_f32_e32 v226, v227
	s_waitcnt vmcnt(8)
	v_mfma_f32_16x16x32_f16 v[8:11], v[228:231], v[0:3], 0
	v_mfma_f32_16x16x32_f16 v[8:11], v[232:235], v[4:7], v[8:11]
	global_load_dwordx4 v[228:231], v85, s[70:71]
	global_load_dwordx4 v[232:235], v85, s[70:71] offset:64
	v_add_u32_e32 v85, 0x4000, v85
	s_nop 4
	v_cndmask_b32_e64 v222, v8, v11, s[40:41]
	v_cndmask_b32_e64 v223, v9, v10, s[40:41]
	v_cndmask_b32_e64 v224, v10, v9, s[40:41]
	v_cndmask_b32_e64 v225, v11, v8, s[40:41]
	v_mul_f32_e32 v222, v222, v226
	v_mul_f32_e32 v223, v223, v226
	v_mul_f32_e32 v224, v224, v226
	v_mul_f32_e32 v225, v225, v226
	v_mul_f32_e32 v222, v80, v222
	v_mul_f32_e32 v223, v81, v223
	v_mul_f32_e32 v224, v82, v224
	v_mul_f32_e32 v225, v84, v225
	v_mul_f32_e32 v31, v222, v222
	v_fmac_f32_e32 v31, v223, v223
	v_fmac_f32_e32 v31, v224, v224
	v_fmac_f32_e32 v31, v225, v225
	v_add_f32_e32 v28, v28, v31
	s_mov_b64 exec, s[38:39]
	ds_write_b32 v78, v222
	ds_write_b32 v78, v223 offset:8
	ds_write_b32 v78, v224 offset:16
	ds_write_b32 v78, v225 offset:24
	s_mov_b64 exec, -1
	v_add_u32_e32 v78, v78, v79
	v_add_u32_e32 v227, 0x1700, v29
	v_cvt_f32_i32_e32 v227, v227
	v_mul_f32_e32 v227, v93, v227
	v_mul_f32_e32 v227, 0x3fb8aa3b, v227
	v_exp_f32_e32 v226, v227
	s_waitcnt vmcnt(8)
	v_mfma_f32_16x16x32_f16 v[8:11], v[236:239], v[0:3], 0
	v_mfma_f32_16x16x32_f16 v[8:11], v[240:243], v[4:7], v[8:11]
	global_load_dwordx4 v[236:239], v85, s[70:71]
	global_load_dwordx4 v[240:243], v85, s[70:71] offset:64
	v_add_u32_e32 v85, 0x4000, v85
	s_nop 4
	v_cndmask_b32_e64 v222, v8, v11, s[40:41]
	v_cndmask_b32_e64 v223, v9, v10, s[40:41]
	v_cndmask_b32_e64 v224, v10, v9, s[40:41]
	v_cndmask_b32_e64 v225, v11, v8, s[40:41]
	v_mul_f32_e32 v222, v222, v226
	v_mul_f32_e32 v223, v223, v226
	v_mul_f32_e32 v224, v224, v226
	v_mul_f32_e32 v225, v225, v226
	v_mul_f32_e32 v222, v80, v222
	v_mul_f32_e32 v223, v81, v223
	v_mul_f32_e32 v224, v82, v224
	v_mul_f32_e32 v225, v84, v225
	v_mul_f32_e32 v31, v222, v222
	v_fmac_f32_e32 v31, v223, v223
	v_fmac_f32_e32 v31, v224, v224
	v_fmac_f32_e32 v31, v225, v225
	v_add_f32_e32 v28, v28, v31
	s_mov_b64 exec, s[38:39]
	ds_write_b32 v78, v222
	ds_write_b32 v78, v223 offset:8
	ds_write_b32 v78, v224 offset:16
	ds_write_b32 v78, v225 offset:24
	s_mov_b64 exec, -1
	v_add_u32_e32 v78, v78, v79
	v_add_u32_e32 v227, 0x1780, v29
	v_cvt_f32_i32_e32 v227, v227
	v_mul_f32_e32 v227, v93, v227
	v_mul_f32_e32 v227, 0x3fb8aa3b, v227
	v_exp_f32_e32 v226, v227
	s_waitcnt vmcnt(8)
	v_mfma_f32_16x16x32_f16 v[8:11], v[244:247], v[0:3], 0
	v_mfma_f32_16x16x32_f16 v[8:11], v[248:251], v[4:7], v[8:11]
	global_load_dwordx4 v[244:247], v85, s[70:71]
	global_load_dwordx4 v[248:251], v85, s[70:71] offset:64
	v_add_u32_e32 v85, 0x4000, v85
	s_nop 4
	v_cndmask_b32_e64 v222, v8, v11, s[40:41]
	v_cndmask_b32_e64 v223, v9, v10, s[40:41]
	v_cndmask_b32_e64 v224, v10, v9, s[40:41]
	v_cndmask_b32_e64 v225, v11, v8, s[40:41]
	v_mul_f32_e32 v222, v222, v226
	v_mul_f32_e32 v223, v223, v226
	v_mul_f32_e32 v224, v224, v226
	v_mul_f32_e32 v225, v225, v226
	v_mul_f32_e32 v222, v80, v222
	v_mul_f32_e32 v223, v81, v223
	v_mul_f32_e32 v224, v82, v224
	v_mul_f32_e32 v225, v84, v225
	v_mul_f32_e32 v31, v222, v222
	v_fmac_f32_e32 v31, v223, v223
	v_fmac_f32_e32 v31, v224, v224
	v_fmac_f32_e32 v31, v225, v225
	v_add_f32_e32 v28, v28, v31
	s_mov_b64 exec, s[38:39]
	ds_write_b32 v78, v222
	ds_write_b32 v78, v223 offset:8
	ds_write_b32 v78, v224 offset:16
	ds_write_b32 v78, v225 offset:24
	s_mov_b64 exec, -1
	v_add_u32_e32 v78, v78, v79
	v_add_u32_e32 v227, 0x1800, v29
	v_cvt_f32_i32_e32 v227, v227
	v_mul_f32_e32 v227, v93, v227
	v_mul_f32_e32 v227, 0x3fb8aa3b, v227
	v_exp_f32_e32 v226, v227
	s_waitcnt vmcnt(8)
; __device__ __forceinline__ void phase_hyena(KP kp_, int hf){ asm volatile("" : "+s"(kp_)); const Params p=load_params(kp_);
;     ...
;       _Pragma("unroll 8") for (int i=0;i<64;++i){ int tl=wid+8*i;
;         const _Float16* ap=a3+(size_t)(tl*16+n)*64+kg*8;
;         f16x8 a0=*(const f16x8*)ap, a1=*(const f16x8*)(ap+32);
;         f32x4 dd={0.f,0.f,0.f,0.f};
;         dd=__builtin_amdgcn_mfma_f32_16x16x32_f16(a0,bw0,dd,0,0,0);
;         dd=__builtin_amdgcn_mfma_f32_16x16x32_f16(a1,bw1,dd,0,0,0);
;         if (n<4){ float d0=__expf(dsc*(float)(tl*16)); int lag0=tl*16+kg*4;
;           float v0=dd[0]*d0*pj0, v1=dd[1]*d0*pj1, v2=dd[2]*d0*pj2, v3=dd[3]*d0*pj3;
;           if (!side1){ Zf[2*(lag0)+order]=v0; Zf[2*(lag0+1)+order]=v1; Zf[2*(lag0+2)+order]=v2; Zf[2*(lag0+3)+order]=v3; ssl+=v0*v0+v1*v1+v2*v2+v3*v3; }
;           else { if (lag0>=1){ Zf[2*(16384-lag0)+order]=v0; ssl+=v0*v0; }
;             Zf[2*(16384-lag0-1)+order]=v1; Zf[2*(16384-lag0-2)+order]=v2; Zf[2*(16384-lag0-3)+order]=v3; ssl+=v1*v1+v2*v2+v3*v3; } }
;       }
	v_mfma_f32_16x16x32_f16 v[8:11], v[12:15], v[0:3], 0
	v_mfma_f32_16x16x32_f16 v[8:11], v[16:19], v[4:7], v[8:11]
	global_load_dwordx4 v[12:15], v85, s[70:71]
	global_load_dwordx4 v[16:19], v85, s[70:71] offset:64
	v_add_u32_e32 v85, 0x4000, v85
	s_nop 4
	v_cndmask_b32_e64 v222, v8, v11, s[40:41]
	v_cndmask_b32_e64 v223, v9, v10, s[40:41]
	v_cndmask_b32_e64 v224, v10, v9, s[40:41]
	v_cndmask_b32_e64 v225, v11, v8, s[40:41]
	v_mul_f32_e32 v222, v222, v226
	v_mul_f32_e32 v223, v223, v226
	v_mul_f32_e32 v224, v224, v226
	v_mul_f32_e32 v225, v225, v226
	v_mul_f32_e32 v222, v80, v222
	v_mul_f32_e32 v223, v81, v223
	v_mul_f32_e32 v224, v82, v224
	v_mul_f32_e32 v225, v84, v225
	v_mul_f32_e32 v31, v222, v222
	v_fmac_f32_e32 v31, v223, v223
	v_fmac_f32_e32 v31, v224, v224
	v_fmac_f32_e32 v31, v225, v225
	v_add_f32_e32 v28, v28, v31
	s_mov_b64 exec, s[38:39]
	ds_write_b32 v78, v222
	ds_write_b32 v78, v223 offset:8
	ds_write_b32 v78, v224 offset:16
	ds_write_b32 v78, v225 offset:24
	s_mov_b64 exec, -1
	v_add_u32_e32 v78, v78, v79
	v_add_u32_e32 v227, 0x1880, v29
	v_cvt_f32_i32_e32 v227, v227
	v_mul_f32_e32 v227, v93, v227
	v_mul_f32_e32 v227, 0x3fb8aa3b, v227
	v_exp_f32_e32 v226, v227
	s_waitcnt vmcnt(8)
	v_mfma_f32_16x16x32_f16 v[8:11], v[20:23], v[0:3], 0
	v_mfma_f32_16x16x32_f16 v[8:11], v[24:27], v[4:7], v[8:11]
	global_load_dwordx4 v[20:23], v85, s[70:71]
	global_load_dwordx4 v[24:27], v85, s[70:71] offset:64
	v_add_u32_e32 v85, 0x4000, v85
	s_nop 4
	v_cndmask_b32_e64 v222, v8, v11, s[40:41]
	v_cndmask_b32_e64 v223, v9, v10, s[40:41]
	v_cndmask_b32_e64 v224, v10, v9, s[40:41]
	v_cndmask_b32_e64 v225, v11, v8, s[40:41]
	v_mul_f32_e32 v222, v222, v226
	v_mul_f32_e32 v223, v223, v226
	v_mul_f32_e32 v224, v224, v226
	v_mul_f32_e32 v225, v225, v226
	v_mul_f32_e32 v222, v80, v222
	v_mul_f32_e32 v223, v81, v223
	v_mul_f32_e32 v224, v82, v224
	v_mul_f32_e32 v225, v84, v225
	v_mul_f32_e32 v31, v222, v222
	v_fmac_f32_e32 v31, v223, v223
	v_fmac_f32_e32 v31, v224, v224
	v_fmac_f32_e32 v31, v225, v225
	v_add_f32_e32 v28, v28, v31
	s_mov_b64 exec, s[38:39]
	ds_write_b32 v78, v222
	ds_write_b32 v78, v223 offset:8
	ds_write_b32 v78, v224 offset:16
	ds_write_b32 v78, v225 offset:24
	s_mov_b64 exec, -1
	v_add_u32_e32 v78, v78, v79
	v_add_u32_e32 v227, 0x1900, v29
	v_cvt_f32_i32_e32 v227, v227
	v_mul_f32_e32 v227, v93, v227
	v_mul_f32_e32 v227, 0x3fb8aa3b, v227
	v_exp_f32_e32 v226, v227
	s_waitcnt vmcnt(8)
	v_mfma_f32_16x16x32_f16 v[8:11], v[228:231], v[0:3], 0
	v_mfma_f32_16x16x32_f16 v[8:11], v[232:235], v[4:7], v[8:11]
	global_load_dwordx4 v[228:231], v85, s[70:71]
	global_load_dwordx4 v[232:235], v85, s[70:71] offset:64
	v_add_u32_e32 v85, 0x4000, v85
	s_nop 4
	v_cndmask_b32_e64 v222, v8, v11, s[40:41]
	v_cndmask_b32_e64 v223, v9, v10, s[40:41]
	v_cndmask_b32_e64 v224, v10, v9, s[40:41]
	v_cndmask_b32_e64 v225, v11, v8, s[40:41]
	v_mul_f32_e32 v222, v222, v226
	v_mul_f32_e32 v223, v223, v226
	v_mul_f32_e32 v224, v224, v226
	v_mul_f32_e32 v225, v225, v226
	v_mul_f32_e32 v222, v80, v222
	v_mul_f32_e32 v223, v81, v223
	v_mul_f32_e32 v224, v82, v224
	v_mul_f32_e32 v225, v84, v225
	v_mul_f32_e32 v31, v222, v222
	v_fmac_f32_e32 v31, v223, v223
	v_fmac_f32_e32 v31, v224, v224
	v_fmac_f32_e32 v31, v225, v225
	v_add_f32_e32 v28, v28, v31
	s_mov_b64 exec, s[38:39]
	ds_write_b32 v78, v222
	ds_write_b32 v78, v223 offset:8
	ds_write_b32 v78, v224 offset:16
	ds_write_b32 v78, v225 offset:24
	s_mov_b64 exec, -1
	v_add_u32_e32 v78, v78, v79
	v_add_u32_e32 v227, 0x1980, v29
	v_cvt_f32_i32_e32 v227, v227
	v_mul_f32_e32 v227, v93, v227
	v_mul_f32_e32 v227, 0x3fb8aa3b, v227
	v_exp_f32_e32 v226, v227
	s_waitcnt vmcnt(8)
	v_mfma_f32_16x16x32_f16 v[8:11], v[236:239], v[0:3], 0
	v_mfma_f32_16x16x32_f16 v[8:11], v[240:243], v[4:7], v[8:11]
	global_load_dwordx4 v[236:239], v85, s[70:71]
	global_load_dwordx4 v[240:243], v85, s[70:71] offset:64
	v_add_u32_e32 v85, 0x4000, v85
	s_nop 4
	v_cndmask_b32_e64 v222, v8, v11, s[40:41]
	v_cndmask_b32_e64 v223, v9, v10, s[40:41]
	v_cndmask_b32_e64 v224, v10, v9, s[40:41]
	v_cndmask_b32_e64 v225, v11, v8, s[40:41]
	v_mul_f32_e32 v222, v222, v226
	v_mul_f32_e32 v223, v223, v226
	v_mul_f32_e32 v224, v224, v226
	v_mul_f32_e32 v225, v225, v226
	v_mul_f32_e32 v222, v80, v222
	v_mul_f32_e32 v223, v81, v223
	v_mul_f32_e32 v224, v82, v224
	v_mul_f32_e32 v225, v84, v225
	v_mul_f32_e32 v31, v222, v222
	v_fmac_f32_e32 v31, v223, v223
	v_fmac_f32_e32 v31, v224, v224
	v_fmac_f32_e32 v31, v225, v225
	v_add_f32_e32 v28, v28, v31
	s_mov_b64 exec, s[38:39]
	ds_write_b32 v78, v222
	ds_write_b32 v78, v223 offset:8
	ds_write_b32 v78, v224 offset:16
	ds_write_b32 v78, v225 offset:24
	s_mov_b64 exec, -1
	v_add_u32_e32 v78, v78, v79
	v_add_u32_e32 v227, 0x1a00, v29
	v_cvt_f32_i32_e32 v227, v227
	v_mul_f32_e32 v227, v93, v227
	v_mul_f32_e32 v227, 0x3fb8aa3b, v227
	v_exp_f32_e32 v226, v227
	s_waitcnt vmcnt(8)
	v_mfma_f32_16x16x32_f16 v[8:11], v[244:247], v[0:3], 0
	v_mfma_f32_16x16x32_f16 v[8:11], v[248:251], v[4:7], v[8:11]
	global_load_dwordx4 v[244:247], v85, s[70:71]
	global_load_dwordx4 v[248:251], v85, s[70:71] offset:64
	v_add_u32_e32 v85, 0x4000, v85
	s_nop 4
	v_cndmask_b32_e64 v222, v8, v11, s[40:41]
	v_cndmask_b32_e64 v223, v9, v10, s[40:41]
	v_cndmask_b32_e64 v224, v10, v9, s[40:41]
	v_cndmask_b32_e64 v225, v11, v8, s[40:41]
	v_mul_f32_e32 v222, v222, v226
	v_mul_f32_e32 v223, v223, v226
	v_mul_f32_e32 v224, v224, v226
	v_mul_f32_e32 v225, v225, v226
	v_mul_f32_e32 v222, v80, v222
	v_mul_f32_e32 v223, v81, v223
	v_mul_f32_e32 v224, v82, v224
	v_mul_f32_e32 v225, v84, v225
	v_mul_f32_e32 v31, v222, v222
	v_fmac_f32_e32 v31, v223, v223
	v_fmac_f32_e32 v31, v224, v224
	v_fmac_f32_e32 v31, v225, v225
	v_add_f32_e32 v28, v28, v31
	s_mov_b64 exec, s[38:39]
	ds_write_b32 v78, v222
	ds_write_b32 v78, v223 offset:8
	ds_write_b32 v78, v224 offset:16
	ds_write_b32 v78, v225 offset:24
	s_mov_b64 exec, -1
	v_add_u32_e32 v78, v78, v79
	v_add_u32_e32 v227, 0x1a80, v29
	v_cvt_f32_i32_e32 v227, v227
	v_mul_f32_e32 v227, v93, v227
	v_mul_f32_e32 v227, 0x3fb8aa3b, v227
	v_exp_f32_e32 v226, v227
	s_waitcnt vmcnt(8)
; __device__ __forceinline__ void phase_hyena(KP kp_, int hf){ asm volatile("" : "+s"(kp_)); const Params p=load_params(kp_);
;     ...
;       _Pragma("unroll 8") for (int i=0;i<64;++i){ int tl=wid+8*i;
;         const _Float16* ap=a3+(size_t)(tl*16+n)*64+kg*8;
;         f16x8 a0=*(const f16x8*)ap, a1=*(const f16x8*)(ap+32);
;         f32x4 dd={0.f,0.f,0.f,0.f};
;         dd=__builtin_amdgcn_mfma_f32_16x16x32_f16(a0,bw0,dd,0,0,0);
;         dd=__builtin_amdgcn_mfma_f32_16x16x32_f16(a1,bw1,dd,0,0,0);
;         if (n<4){ float d0=__expf(dsc*(float)(tl*16)); int lag0=tl*16+kg*4;
;           float v0=dd[0]*d0*pj0, v1=dd[1]*d0*pj1, v2=dd[2]*d0*pj2, v3=dd[3]*d0*pj3;
;           if (!side1){ Zf[2*(lag0)+order]=v0; Zf[2*(lag0+1)+order]=v1; Zf[2*(lag0+2)+order]=v2; Zf[2*(lag0+3)+order]=v3; ssl+=v0*v0+v1*v1+v2*v2+v3*v3; }
;           else { if (lag0>=1){ Zf[2*(16384-lag0)+order]=v0; ssl+=v0*v0; }
;             Zf[2*(16384-lag0-1)+order]=v1; Zf[2*(16384-lag0-2)+order]=v2; Zf[2*(16384-lag0-3)+order]=v3; ssl+=v1*v1+v2*v2+v3*v3; } }
;       }
	v_mfma_f32_16x16x32_f16 v[8:11], v[12:15], v[0:3], 0
	v_mfma_f32_16x16x32_f16 v[8:11], v[16:19], v[4:7], v[8:11]
	global_load_dwordx4 v[12:15], v85, s[70:71]
	global_load_dwordx4 v[16:19], v85, s[70:71] offset:64
	v_add_u32_e32 v85, 0x4000, v85
	s_nop 4
	v_cndmask_b32_e64 v222, v8, v11, s[40:41]
	v_cndmask_b32_e64 v223, v9, v10, s[40:41]
	v_cndmask_b32_e64 v224, v10, v9, s[40:41]
	v_cndmask_b32_e64 v225, v11, v8, s[40:41]
	v_mul_f32_e32 v222, v222, v226
	v_mul_f32_e32 v223, v223, v226
	v_mul_f32_e32 v224, v224, v226
	v_mul_f32_e32 v225, v225, v226
	v_mul_f32_e32 v222, v80, v222
	v_mul_f32_e32 v223, v81, v223
	v_mul_f32_e32 v224, v82, v224
	v_mul_f32_e32 v225, v84, v225
	v_mul_f32_e32 v31, v222, v222
	v_fmac_f32_e32 v31, v223, v223
	v_fmac_f32_e32 v31, v224, v224
	v_fmac_f32_e32 v31, v225, v225
	v_add_f32_e32 v28, v28, v31
	s_mov_b64 exec, s[38:39]
	ds_write_b32 v78, v222
	ds_write_b32 v78, v223 offset:8
	ds_write_b32 v78, v224 offset:16
	ds_write_b32 v78, v225 offset:24
	s_mov_b64 exec, -1
	v_add_u32_e32 v78, v78, v79
	v_add_u32_e32 v227, 0x1b00, v29
	v_cvt_f32_i32_e32 v227, v227
	v_mul_f32_e32 v227, v93, v227
	v_mul_f32_e32 v227, 0x3fb8aa3b, v227
	v_exp_f32_e32 v226, v227
	s_waitcnt vmcnt(8)
	v_mfma_f32_16x16x32_f16 v[8:11], v[20:23], v[0:3], 0
	v_mfma_f32_16x16x32_f16 v[8:11], v[24:27], v[4:7], v[8:11]
	global_load_dwordx4 v[20:23], v85, s[70:71]
	global_load_dwordx4 v[24:27], v85, s[70:71] offset:64
	v_add_u32_e32 v85, 0x4000, v85
	s_nop 4
	v_cndmask_b32_e64 v222, v8, v11, s[40:41]
	v_cndmask_b32_e64 v223, v9, v10, s[40:41]
	v_cndmask_b32_e64 v224, v10, v9, s[40:41]
	v_cndmask_b32_e64 v225, v11, v8, s[40:41]
	v_mul_f32_e32 v222, v222, v226
	v_mul_f32_e32 v223, v223, v226
	v_mul_f32_e32 v224, v224, v226
	v_mul_f32_e32 v225, v225, v226
	v_mul_f32_e32 v222, v80, v222
	v_mul_f32_e32 v223, v81, v223
	v_mul_f32_e32 v224, v82, v224
	v_mul_f32_e32 v225, v84, v225
	v_mul_f32_e32 v31, v222, v222
	v_fmac_f32_e32 v31, v223, v223
	v_fmac_f32_e32 v31, v224, v224
	v_fmac_f32_e32 v31, v225, v225
	v_add_f32_e32 v28, v28, v31
	s_mov_b64 exec, s[38:39]
	ds_write_b32 v78, v222
	ds_write_b32 v78, v223 offset:8
	ds_write_b32 v78, v224 offset:16
	ds_write_b32 v78, v225 offset:24
	s_mov_b64 exec, -1
	v_add_u32_e32 v78, v78, v79
	v_add_u32_e32 v227, 0x1b80, v29
	v_cvt_f32_i32_e32 v227, v227
	v_mul_f32_e32 v227, v93, v227
	v_mul_f32_e32 v227, 0x3fb8aa3b, v227
	v_exp_f32_e32 v226, v227
	s_waitcnt vmcnt(8)
	v_mfma_f32_16x16x32_f16 v[8:11], v[228:231], v[0:3], 0
	v_mfma_f32_16x16x32_f16 v[8:11], v[232:235], v[4:7], v[8:11]
	global_load_dwordx4 v[228:231], v85, s[70:71]
	global_load_dwordx4 v[232:235], v85, s[70:71] offset:64
	v_add_u32_e32 v85, 0x4000, v85
	s_nop 4
	v_cndmask_b32_e64 v222, v8, v11, s[40:41]
	v_cndmask_b32_e64 v223, v9, v10, s[40:41]
	v_cndmask_b32_e64 v224, v10, v9, s[40:41]
	v_cndmask_b32_e64 v225, v11, v8, s[40:41]
	v_mul_f32_e32 v222, v222, v226
	v_mul_f32_e32 v223, v223, v226
	v_mul_f32_e32 v224, v224, v226
	v_mul_f32_e32 v225, v225, v226
	v_mul_f32_e32 v222, v80, v222
	v_mul_f32_e32 v223, v81, v223
	v_mul_f32_e32 v224, v82, v224
	v_mul_f32_e32 v225, v84, v225
	v_mul_f32_e32 v31, v222, v222
	v_fmac_f32_e32 v31, v223, v223
	v_fmac_f32_e32 v31, v224, v224
	v_fmac_f32_e32 v31, v225, v225
	v_add_f32_e32 v28, v28, v31
	s_mov_b64 exec, s[38:39]
	ds_write_b32 v78, v222
	ds_write_b32 v78, v223 offset:8
	ds_write_b32 v78, v224 offset:16
	ds_write_b32 v78, v225 offset:24
	s_mov_b64 exec, -1
	v_add_u32_e32 v78, v78, v79
	v_add_u32_e32 v227, 0x1c00, v29
	v_cvt_f32_i32_e32 v227, v227
	v_mul_f32_e32 v227, v93, v227
	v_mul_f32_e32 v227, 0x3fb8aa3b, v227
	v_exp_f32_e32 v226, v227
	s_waitcnt vmcnt(8)
	v_mfma_f32_16x16x32_f16 v[8:11], v[236:239], v[0:3], 0
	v_mfma_f32_16x16x32_f16 v[8:11], v[240:243], v[4:7], v[8:11]
	global_load_dwordx4 v[236:239], v85, s[70:71]
	global_load_dwordx4 v[240:243], v85, s[70:71] offset:64
	v_add_u32_e32 v85, 0x4000, v85
	s_nop 4
	v_cndmask_b32_e64 v222, v8, v11, s[40:41]
	v_cndmask_b32_e64 v223, v9, v10, s[40:41]
	v_cndmask_b32_e64 v224, v10, v9, s[40:41]
	v_cndmask_b32_e64 v225, v11, v8, s[40:41]
	v_mul_f32_e32 v222, v222, v226
	v_mul_f32_e32 v223, v223, v226
	v_mul_f32_e32 v224, v224, v226
	v_mul_f32_e32 v225, v225, v226
	v_mul_f32_e32 v222, v80, v222
	v_mul_f32_e32 v223, v81, v223
	v_mul_f32_e32 v224, v82, v224
	v_mul_f32_e32 v225, v84, v225
	v_mul_f32_e32 v31, v222, v222
	v_fmac_f32_e32 v31, v223, v223
	v_fmac_f32_e32 v31, v224, v224
	v_fmac_f32_e32 v31, v225, v225
	v_add_f32_e32 v28, v28, v31
	s_mov_b64 exec, s[38:39]
	ds_write_b32 v78, v222
	ds_write_b32 v78, v223 offset:8
	ds_write_b32 v78, v224 offset:16
	ds_write_b32 v78, v225 offset:24
	s_mov_b64 exec, -1
	v_add_u32_e32 v78, v78, v79
	v_add_u32_e32 v227, 0x1c80, v29
	v_cvt_f32_i32_e32 v227, v227
	v_mul_f32_e32 v227, v93, v227
	v_mul_f32_e32 v227, 0x3fb8aa3b, v227
	v_exp_f32_e32 v226, v227
	s_waitcnt vmcnt(8)
	v_mfma_f32_16x16x32_f16 v[8:11], v[244:247], v[0:3], 0
	v_mfma_f32_16x16x32_f16 v[8:11], v[248:251], v[4:7], v[8:11]
	global_load_dwordx4 v[244:247], v85, s[70:71]
	global_load_dwordx4 v[248:251], v85, s[70:71] offset:64
	v_add_u32_e32 v85, 0x4000, v85
	s_nop 4
	v_cndmask_b32_e64 v222, v8, v11, s[40:41]
	v_cndmask_b32_e64 v223, v9, v10, s[40:41]
	v_cndmask_b32_e64 v224, v10, v9, s[40:41]
	v_cndmask_b32_e64 v225, v11, v8, s[40:41]
	v_mul_f32_e32 v222, v222, v226
	v_mul_f32_e32 v223, v223, v226
	v_mul_f32_e32 v224, v224, v226
	v_mul_f32_e32 v225, v225, v226
	v_mul_f32_e32 v222, v80, v222
	v_mul_f32_e32 v223, v81, v223
	v_mul_f32_e32 v224, v82, v224
	v_mul_f32_e32 v225, v84, v225
	v_mul_f32_e32 v31, v222, v222
	v_fmac_f32_e32 v31, v223, v223
	v_fmac_f32_e32 v31, v224, v224
	v_fmac_f32_e32 v31, v225, v225
	v_add_f32_e32 v28, v28, v31
	s_mov_b64 exec, s[38:39]
	ds_write_b32 v78, v222
	ds_write_b32 v78, v223 offset:8
	ds_write_b32 v78, v224 offset:16
	ds_write_b32 v78, v225 offset:24
	s_mov_b64 exec, -1
	v_add_u32_e32 v78, v78, v79
	v_add_u32_e32 v227, 0x1d00, v29
	v_cvt_f32_i32_e32 v227, v227
	v_mul_f32_e32 v227, v93, v227
	v_mul_f32_e32 v227, 0x3fb8aa3b, v227
	v_exp_f32_e32 v226, v227
	s_waitcnt vmcnt(8)
; __device__ __forceinline__ void phase_hyena(KP kp_, int hf){ asm volatile("" : "+s"(kp_)); const Params p=load_params(kp_);
;     ...
;       _Pragma("unroll 8") for (int i=0;i<64;++i){ int tl=wid+8*i;
;         const _Float16* ap=a3+(size_t)(tl*16+n)*64+kg*8;
;         f16x8 a0=*(const f16x8*)ap, a1=*(const f16x8*)(ap+32);
;         f32x4 dd={0.f,0.f,0.f,0.f};
;         dd=__builtin_amdgcn_mfma_f32_16x16x32_f16(a0,bw0,dd,0,0,0);
;         dd=__builtin_amdgcn_mfma_f32_16x16x32_f16(a1,bw1,dd,0,0,0);
;         if (n<4){ float d0=__expf(dsc*(float)(tl*16)); int lag0=tl*16+kg*4;
;           float v0=dd[0]*d0*pj0, v1=dd[1]*d0*pj1, v2=dd[2]*d0*pj2, v3=dd[3]*d0*pj3;
;           if (!side1){ Zf[2*(lag0)+order]=v0; Zf[2*(lag0+1)+order]=v1; Zf[2*(lag0+2)+order]=v2; Zf[2*(lag0+3)+order]=v3; ssl+=v0*v0+v1*v1+v2*v2+v3*v3; }
;           else { if (lag0>=1){ Zf[2*(16384-lag0)+order]=v0; ssl+=v0*v0; }
;             Zf[2*(16384-lag0-1)+order]=v1; Zf[2*(16384-lag0-2)+order]=v2; Zf[2*(16384-lag0-3)+order]=v3; ssl+=v1*v1+v2*v2+v3*v3; } }
;       }
;     ...
;     if (tid==0) Z[8192]=make_float2(0.f,0.f);
	v_mfma_f32_16x16x32_f16 v[8:11], v[12:15], v[0:3], 0
	v_mfma_f32_16x16x32_f16 v[8:11], v[16:19], v[4:7], v[8:11]
	global_load_dwordx4 v[12:15], v85, s[70:71]
	global_load_dwordx4 v[16:19], v85, s[70:71] offset:64
	v_add_u32_e32 v85, 0x4000, v85
	s_nop 4
	v_cndmask_b32_e64 v222, v8, v11, s[40:41]
	v_cndmask_b32_e64 v223, v9, v10, s[40:41]
	v_cndmask_b32_e64 v224, v10, v9, s[40:41]
	v_cndmask_b32_e64 v225, v11, v8, s[40:41]
	v_mul_f32_e32 v222, v222, v226
	v_mul_f32_e32 v223, v223, v226
	v_mul_f32_e32 v224, v224, v226
	v_mul_f32_e32 v225, v225, v226
	v_mul_f32_e32 v222, v80, v222
	v_mul_f32_e32 v223, v81, v223
	v_mul_f32_e32 v224, v82, v224
	v_mul_f32_e32 v225, v84, v225
	v_mul_f32_e32 v31, v222, v222
	v_fmac_f32_e32 v31, v223, v223
	v_fmac_f32_e32 v31, v224, v224
	v_fmac_f32_e32 v31, v225, v225
	v_add_f32_e32 v28, v28, v31
	s_mov_b64 exec, s[38:39]
	ds_write_b32 v78, v222
	ds_write_b32 v78, v223 offset:8
	ds_write_b32 v78, v224 offset:16
	ds_write_b32 v78, v225 offset:24
	s_mov_b64 exec, -1
	v_add_u32_e32 v78, v78, v79
	v_add_u32_e32 v227, 0x1d80, v29
	v_cvt_f32_i32_e32 v227, v227
	v_mul_f32_e32 v227, v93, v227
	v_mul_f32_e32 v227, 0x3fb8aa3b, v227
	v_exp_f32_e32 v226, v227
	s_waitcnt vmcnt(8)
	v_mfma_f32_16x16x32_f16 v[8:11], v[20:23], v[0:3], 0
	v_mfma_f32_16x16x32_f16 v[8:11], v[24:27], v[4:7], v[8:11]
	s_nop 2
	s_nop 4
	v_cndmask_b32_e64 v222, v8, v11, s[40:41]
	v_cndmask_b32_e64 v223, v9, v10, s[40:41]
	v_cndmask_b32_e64 v224, v10, v9, s[40:41]
	v_cndmask_b32_e64 v225, v11, v8, s[40:41]
	v_mul_f32_e32 v222, v222, v226
	v_mul_f32_e32 v223, v223, v226
	v_mul_f32_e32 v224, v224, v226
	v_mul_f32_e32 v225, v225, v226
	v_mul_f32_e32 v222, v80, v222
	v_mul_f32_e32 v223, v81, v223
	v_mul_f32_e32 v224, v82, v224
	v_mul_f32_e32 v225, v84, v225
	v_mul_f32_e32 v31, v222, v222
	v_fmac_f32_e32 v31, v223, v223
	v_fmac_f32_e32 v31, v224, v224
	v_fmac_f32_e32 v31, v225, v225
	v_add_f32_e32 v28, v28, v31
	s_mov_b64 exec, s[38:39]
	ds_write_b32 v78, v222
	ds_write_b32 v78, v223 offset:8
	ds_write_b32 v78, v224 offset:16
	ds_write_b32 v78, v225 offset:24
	s_mov_b64 exec, -1
	v_add_u32_e32 v78, v78, v79
	v_add_u32_e32 v227, 0x1e00, v29
	v_cvt_f32_i32_e32 v227, v227
	v_mul_f32_e32 v227, v93, v227
	v_mul_f32_e32 v227, 0x3fb8aa3b, v227
	v_exp_f32_e32 v226, v227
	s_waitcnt vmcnt(6)
	v_mfma_f32_16x16x32_f16 v[8:11], v[228:231], v[0:3], 0
	v_mfma_f32_16x16x32_f16 v[8:11], v[232:235], v[4:7], v[8:11]
	s_nop 2
	s_nop 4
	v_cndmask_b32_e64 v222, v8, v11, s[40:41]
	v_cndmask_b32_e64 v223, v9, v10, s[40:41]
	v_cndmask_b32_e64 v224, v10, v9, s[40:41]
	v_cndmask_b32_e64 v225, v11, v8, s[40:41]
	v_mul_f32_e32 v222, v222, v226
	v_mul_f32_e32 v223, v223, v226
	v_mul_f32_e32 v224, v224, v226
	v_mul_f32_e32 v225, v225, v226
	v_mul_f32_e32 v222, v80, v222
	v_mul_f32_e32 v223, v81, v223
	v_mul_f32_e32 v224, v82, v224
	v_mul_f32_e32 v225, v84, v225
	v_mul_f32_e32 v31, v222, v222
	v_fmac_f32_e32 v31, v223, v223
	v_fmac_f32_e32 v31, v224, v224
	v_fmac_f32_e32 v31, v225, v225
	v_add_f32_e32 v28, v28, v31
	s_mov_b64 exec, s[38:39]
	ds_write_b32 v78, v222
	ds_write_b32 v78, v223 offset:8
	ds_write_b32 v78, v224 offset:16
	ds_write_b32 v78, v225 offset:24
	s_mov_b64 exec, -1
	v_add_u32_e32 v78, v78, v79
	v_add_u32_e32 v227, 0x1e80, v29
	v_cvt_f32_i32_e32 v227, v227
	v_mul_f32_e32 v227, v93, v227
	v_mul_f32_e32 v227, 0x3fb8aa3b, v227
	v_exp_f32_e32 v226, v227
	s_waitcnt vmcnt(4)
	v_mfma_f32_16x16x32_f16 v[8:11], v[236:239], v[0:3], 0
	v_mfma_f32_16x16x32_f16 v[8:11], v[240:243], v[4:7], v[8:11]
	s_nop 2
	s_nop 4
	v_cndmask_b32_e64 v222, v8, v11, s[40:41]
	v_cndmask_b32_e64 v223, v9, v10, s[40:41]
	v_cndmask_b32_e64 v224, v10, v9, s[40:41]
	v_cndmask_b32_e64 v225, v11, v8, s[40:41]
	v_mul_f32_e32 v222, v222, v226
	v_mul_f32_e32 v223, v223, v226
	v_mul_f32_e32 v224, v224, v226
	v_mul_f32_e32 v225, v225, v226
	v_mul_f32_e32 v222, v80, v222
	v_mul_f32_e32 v223, v81, v223
	v_mul_f32_e32 v224, v82, v224
	v_mul_f32_e32 v225, v84, v225
	v_mul_f32_e32 v31, v222, v222
	v_fmac_f32_e32 v31, v223, v223
	v_fmac_f32_e32 v31, v224, v224
	v_fmac_f32_e32 v31, v225, v225
	v_add_f32_e32 v28, v28, v31
	s_mov_b64 exec, s[38:39]
	ds_write_b32 v78, v222
	ds_write_b32 v78, v223 offset:8
	ds_write_b32 v78, v224 offset:16
	ds_write_b32 v78, v225 offset:24
	s_mov_b64 exec, -1
	v_add_u32_e32 v78, v78, v79
	v_add_u32_e32 v227, 0x1f00, v29
	v_cvt_f32_i32_e32 v227, v227
	v_mul_f32_e32 v227, v93, v227
	v_mul_f32_e32 v227, 0x3fb8aa3b, v227
	v_exp_f32_e32 v226, v227
	s_waitcnt vmcnt(2)
	v_mfma_f32_16x16x32_f16 v[8:11], v[244:247], v[0:3], 0
	v_mfma_f32_16x16x32_f16 v[8:11], v[248:251], v[4:7], v[8:11]
	s_nop 2
	s_nop 4
	v_cndmask_b32_e64 v222, v8, v11, s[40:41]
	v_cndmask_b32_e64 v223, v9, v10, s[40:41]
	v_cndmask_b32_e64 v224, v10, v9, s[40:41]
	v_cndmask_b32_e64 v225, v11, v8, s[40:41]
	v_mul_f32_e32 v222, v222, v226
	v_mul_f32_e32 v223, v223, v226
	v_mul_f32_e32 v224, v224, v226
	v_mul_f32_e32 v225, v225, v226
	v_mul_f32_e32 v222, v80, v222
	v_mul_f32_e32 v223, v81, v223
	v_mul_f32_e32 v224, v82, v224
	v_mul_f32_e32 v225, v84, v225
	v_mul_f32_e32 v31, v222, v222
	v_fmac_f32_e32 v31, v223, v223
	v_fmac_f32_e32 v31, v224, v224
	v_fmac_f32_e32 v31, v225, v225
	v_add_f32_e32 v28, v28, v31
	s_mov_b64 exec, s[38:39]
	ds_write_b32 v78, v222
	ds_write_b32 v78, v223 offset:8
	ds_write_b32 v78, v224 offset:16
	ds_write_b32 v78, v225 offset:24
	s_mov_b64 exec, -1
	v_add_u32_e32 v78, v78, v79
	v_add_u32_e32 v227, 0x1f80, v29
	v_cvt_f32_i32_e32 v227, v227
	v_mul_f32_e32 v227, v93, v227
	v_mul_f32_e32 v227, 0x3fb8aa3b, v227
	v_exp_f32_e32 v226, v227
	s_waitcnt vmcnt(0)
	v_mfma_f32_16x16x32_f16 v[8:11], v[12:15], v[0:3], 0
	v_mfma_f32_16x16x32_f16 v[8:11], v[16:19], v[4:7], v[8:11]
	s_nop 2
	s_nop 4
	v_cndmask_b32_e64 v222, v8, v11, s[40:41]
	v_cndmask_b32_e64 v223, v9, v10, s[40:41]
	v_cndmask_b32_e64 v224, v10, v9, s[40:41]
	v_cndmask_b32_e64 v225, v11, v8, s[40:41]
	v_mul_f32_e32 v222, v222, v226
	v_mul_f32_e32 v223, v223, v226
	v_mul_f32_e32 v224, v224, v226
	v_mul_f32_e32 v225, v225, v226
	v_mul_f32_e32 v222, v80, v222
	v_mul_f32_e32 v223, v81, v223
	v_mul_f32_e32 v224, v82, v224
	v_mul_f32_e32 v225, v84, v225
	v_mul_f32_e32 v31, v222, v222
	v_fmac_f32_e32 v31, v223, v223
	v_fmac_f32_e32 v31, v224, v224
	v_fmac_f32_e32 v31, v225, v225
	v_add_f32_e32 v28, v28, v31
	s_mov_b64 exec, s[38:39]
	ds_write_b32 v78, v222
	ds_write_b32 v78, v223 offset:8
	ds_write_b32 v78, v224 offset:16
	ds_write_b32 v78, v225 offset:24
	s_mov_b64 exec, -1
	v_add_u32_e32 v78, v78, v79
	s_waitcnt lgkmcnt(0)
	s_and_saveexec_b64 s[12:13], s[46:47]
	s_cbranch_execz .LBB0_1316
	v_readlane_b32 s18, v253, 23
	s_nop 1
	v_mov_b32_e32 v0, s18
	ds_write_b64 v0, v[220:221]
